# attention tasks: eight K/V staging loads issued together (was four load-wait-write rounds) and their block barrier moved after the loads; gMLP second GV chunk load hoisted
# speedup vs baseline: 1.0423x; 1.0016x over previous
.LBB0_1024:
	s_or_b64 exec, exec, s[4:5]
	s_lshl_b32 s6, s6, 6
	v_and_b32_e32 v17, 7, v16
	v_lshl_or_b32 v24, v17, 3, s6
	v_lshlrev_b32_e32 v136, 1, v24
	v_lshl_add_u64 v[18:19], s[0:1], 0, v[136:137]
	s_mov_b64 s[4:5], 0x3a01a00
	v_ashrrev_i32_e32 v26, 3, v16
	v_lshl_add_u64 v[22:23], v[18:19], 0, s[4:5]
	v_add_u32_e32 v18, s96, v26
	v_mad_i64_i32 v[18:19], s[4:5], v18, s53, v[22:23]
	s_waitcnt lgkmcnt(0)
	s_barrier
	flat_load_dwordx4 v[18:21], v[18:19]
	v_readlane_b32 s8, v255, 12
	v_lshlrev_b32_e32 v24, 2, v24
	v_readlane_b32 s10, v255, 14
	v_readlane_b32 s11, v255, 15
	v_readlane_b32 s12, v255, 16
	v_readlane_b32 s13, v255, 17
	s_nop 2
	global_load_dwordx4 v[32:35], v24, s[10:11]
	s_nop 0
	global_load_dwordx4 v[40:43], v24, s[12:13]
	global_load_dwordx4 v[36:39], v24, s[10:11] offset:16
	global_load_dwordx4 v[44:47], v24, s[12:13] offset:16
	v_add_u32_e32 v24, 0x200, v16
	v_lshl_add_u32 v72, v17, 4, 16
	v_lshl_add_u32 v17, v26, 2, 16
	v_ashrrev_i32_e32 v80, 3, v24
	ds_read2st64_b32 v[24:25], v17 offset1:2
	v_mad_u64_u32 v[26:27], s[4:5], v26, s52, v[72:73]
	v_add_u32_e32 v17, s96, v80
	v_mad_i64_i32 v[22:23], s[4:5], v17, s53, v[22:23]
	flat_load_dwordx4 v[74:77], v[22:23]
	s_waitcnt lgkmcnt(0)
	v_mov_b32_e32 v28, v25
	v_lshl_add_u32 v78, v80, 2, 16
	v_lshlrev_b32_e32 v81, 3, v16
	v_and_b32_e32 v82, 24, v81
	v_mad_u64_u32 v[80:81], s[4:5], v80, s52, v[72:73]
	v_cmp_lt_i32_e32 vcc, -1, v73
	v_mov_b32_e32 v50, 0
	v_mov_b32_e32 v51, 0
	v_mov_b32_e32 v27, 0
	v_mov_b32_e32 v17, 0
	v_readlane_b32 s9, v255, 13
	v_readlane_b32 s14, v255, 18
	v_readlane_b32 s15, v255, 19
	v_readlane_b32 s16, v255, 20
	v_readlane_b32 s17, v255, 21
	v_readlane_b32 s18, v255, 22
	v_readlane_b32 s19, v255, 23
	v_readlane_b32 s20, v255, 24
	v_readlane_b32 s21, v255, 25
	v_readlane_b32 s22, v255, 26
	v_readlane_b32 s23, v255, 27
	s_waitcnt vmcnt(0)
	v_lshlrev_b32_e32 v30, 16, v18
	v_and_b32_e32 v31, 0xffff0000, v18
	v_lshlrev_b32_e32 v18, 16, v19
	v_and_b32_e32 v19, 0xffff0000, v19
	v_lshlrev_b32_e32 v48, 16, v20
	v_and_b32_e32 v49, 0xffff0000, v20
	v_lshlrev_b32_e32 v20, 16, v21
	v_and_b32_e32 v21, 0xffff0000, v21
	v_pk_add_f32 v[30:31], v[30:31], v[24:25] op_sel_hi:[1,0] neg_lo:[0,1] neg_hi:[0,1]
	v_pk_add_f32 v[18:19], v[18:19], v[24:25] op_sel_hi:[1,0] neg_lo:[0,1] neg_hi:[0,1]
	v_pk_add_f32 v[48:49], v[48:49], v[24:25] op_sel_hi:[1,0] neg_lo:[0,1] neg_hi:[0,1]
	v_pk_add_f32 v[20:21], v[20:21], v[24:25] op_sel_hi:[1,0] neg_lo:[0,1] neg_hi:[0,1]
	v_pk_mul_f32 v[24:25], v[30:31], v[28:29] op_sel_hi:[1,0]
	v_pk_mul_f32 v[18:19], v[18:19], v[28:29] op_sel_hi:[1,0]
	v_pk_mul_f32 v[30:31], v[48:49], v[28:29] op_sel_hi:[1,0]
	v_pk_mul_f32 v[20:21], v[20:21], v[28:29] op_sel_hi:[1,0]
	v_pk_fma_f32 v[24:25], v[32:33], v[24:25], v[40:41]
	v_pk_fma_f32 v[28:29], v[34:35], v[18:19], v[42:43]
	v_pk_fma_f32 v[30:31], v[36:37], v[30:31], v[44:45]
	v_pk_fma_f32 v[48:49], v[38:39], v[20:21], v[46:47]
	v_cvt_pk_bf16_f32 v18, v24, v25
	v_cvt_pk_bf16_f32 v19, v28, v29
	v_cvt_pk_bf16_f32 v20, v30, v31
	v_cvt_pk_bf16_f32 v21, v48, v49
	ds_write_b128 v26, v[18:21] offset:1024
	ds_read2st64_b32 v[78:79], v78 offset1:2
	v_bfe_u32 v31, v16, 2, 4
	v_mad_u32_u24 v31, v31, s52, 16
	v_add_u32_e32 v72, v31, v82
	v_mov_b32_e32 v48, 0
	s_waitcnt lgkmcnt(0)
	v_mov_b32_e32 v82, v79
	v_mov_b32_e32 v49, 0
	v_mov_b32_e32 v24, 0
	v_mov_b32_e32 v25, 0
	v_mov_b32_e32 v26, 0
	v_mov_b32_e32 v16, 0
	v_mov_b32_e32 v18, 0
	v_mov_b32_e32 v19, 0
	v_mov_b32_e32 v20, 0
	v_mov_b32_e32 v21, 0
	v_mov_b32_e32 v22, 0
	v_mov_b32_e32 v23, 0
	v_mov_b32_e32 v28, 0
	v_mov_b32_e32 v29, 0
	v_mov_b32_e32 v30, 0
	v_mov_b32_e32 v31, 0
	s_waitcnt vmcnt(0)
	v_lshlrev_b32_e32 v84, 16, v74
	v_and_b32_e32 v85, 0xffff0000, v74
	v_lshlrev_b32_e32 v74, 16, v75
	v_and_b32_e32 v75, 0xffff0000, v75
	v_lshlrev_b32_e32 v86, 16, v76
	v_and_b32_e32 v87, 0xffff0000, v76
	v_lshlrev_b32_e32 v76, 16, v77
	v_and_b32_e32 v77, 0xffff0000, v77
	v_pk_add_f32 v[84:85], v[84:85], v[78:79] op_sel_hi:[1,0] neg_lo:[0,1] neg_hi:[0,1]
	v_pk_add_f32 v[74:75], v[74:75], v[78:79] op_sel_hi:[1,0] neg_lo:[0,1] neg_hi:[0,1]
	v_pk_add_f32 v[86:87], v[86:87], v[78:79] op_sel_hi:[1,0] neg_lo:[0,1] neg_hi:[0,1]
	v_pk_add_f32 v[76:77], v[76:77], v[78:79] op_sel_hi:[1,0] neg_lo:[0,1] neg_hi:[0,1]
	v_pk_mul_f32 v[78:79], v[84:85], v[82:83] op_sel_hi:[1,0]
	v_pk_mul_f32 v[74:75], v[74:75], v[82:83] op_sel_hi:[1,0]
	v_pk_mul_f32 v[84:85], v[86:87], v[82:83] op_sel_hi:[1,0]
	v_pk_mul_f32 v[76:77], v[82:83], v[76:77] op_sel_hi:[0,1]
	v_pk_fma_f32 v[32:33], v[32:33], v[78:79], v[40:41]
	v_pk_fma_f32 v[34:35], v[34:35], v[74:75], v[42:43]
	v_pk_fma_f32 v[36:37], v[36:37], v[84:85], v[44:45]
	v_pk_fma_f32 v[38:39], v[38:39], v[76:77], v[46:47]
	v_cvt_pk_bf16_f32 v32, v32, v33
	v_cvt_pk_bf16_f32 v33, v34, v35
	v_cvt_pk_bf16_f32 v34, v36, v37
	v_cvt_pk_bf16_f32 v35, v38, v39
	ds_write_b128 v80, v[32:35] offset:1024
	s_waitcnt lgkmcnt(0)
	s_barrier
	s_and_saveexec_b64 s[4:5], vcc
	s_cbranch_execz .LBB0_1026
	ds_read_b64_tr_b16 v[16:17], v72 offset:1024
	ds_read_b64_tr_b16 v[18:19], v72 offset:3584
	ds_read_b64_tr_b16 v[22:23], v72 offset:3616
	ds_read_b64_tr_b16 v[20:21], v72 offset:1056
	ds_read_b64_tr_b16 v[32:33], v72 offset:1088
	ds_read_b64_tr_b16 v[28:29], v72 offset:1120
	ds_read_b64_tr_b16 v[34:35], v72 offset:3648
	ds_read_b64_tr_b16 v[30:31], v72 offset:3680
	s_waitcnt lgkmcnt(6)
	v_mfma_f32_16x16x32_bf16 v[24:27], v[16:19], v[12:15], 0
	s_waitcnt lgkmcnt(0)
	v_mfma_f32_16x16x32_bf16 v[48:51], v[28:31], v[12:15], 0
	v_mfma_f32_16x16x32_bf16 v[16:19], v[20:23], v[12:15], 0
	v_mfma_f32_16x16x32_bf16 v[20:23], v[32:35], v[12:15], 0
	s_nop 5
	v_mov_b32_e32 v28, v48
	v_mov_b32_e32 v29, v49
	v_mov_b32_e32 v30, v50
	v_mov_b32_e32 v31, v51

.LBB0_1034:
	s_andn2_b64 vcc, exec, s[0:1]
	s_cbranch_vccnz .LBB0_1036
	s_add_i32 s4, s56, 0xfffffd00
	s_lshr_b32 s8, s4, 8
	s_lshl_b32 s4, s4, 7
	s_lshl_b32 s5, s8, 13
	s_and_b32 s4, s4, 0x1f80
	s_or_b32 s96, s5, s4
	s_mov_b64 s[0:1], s[38:39]
	v_mov_b32_e32 v82, v192
	s_bfe_u32 s9, s56, 0x20006
	s_lshl_b64 s[4:5], s[96:97], 9
	s_add_u32 s6, s0, s4
	v_ashrrev_i32_e32 v0, 2, v82
	s_addc_u32 s7, s1, s5
	s_lshl_b32 s4, s9, 7
	v_and_b32_e32 v8, -16, v0
	v_bfi_b32 v52, -16, v0, v82
	s_add_u32 s6, s6, s4
	v_ashrrev_i32_e32 v53, 31, v52
	v_ashrrev_i32_e32 v9, 31, v8
	v_and_b32_e32 v34, 15, v82
	v_bfe_u32 v83, v82, 4, 2
	s_addc_u32 s7, s7, 0
	v_lshlrev_b64 v[0:1], 9, v[52:53]
	v_lshl_add_u64 v[8:9], v[8:9], 0, s[96:97]
	v_lshl_add_u64 v[0:1], s[6:7], 0, v[0:1]
	v_lshlrev_b32_e32 v16, 4, v83
	v_mov_b32_e32 v17, v137
	v_or_b32_e32 v8, v8, v34
	v_lshl_add_u64 v[0:1], v[0:1], 0, v[16:17]
	s_mov_b64 s[6:7], 0x868da00
	v_lshlrev_b64 v[8:9], 9, v[8:9]
	s_mov_b32 s5, s97
	s_waitcnt lgkmcnt(0)
	v_lshl_add_u64 v[2:3], v[0:1], 0, s[6:7]
	s_mov_b32 s6, 0x868d000
	v_lshl_add_u64 v[8:9], s[0:1], 0, v[8:9]
	v_lshlrev_b32_e32 v136, 3, v83
	v_add_co_u32_e32 v0, vcc, s6, v0
	v_lshl_add_u64 v[8:9], v[8:9], 0, s[4:5]
	s_nop 0
	v_addc_co_u32_e32 v1, vcc, 0, v1, vcc
	v_lshl_add_u64 v[8:9], v[8:9], 0, v[136:137]
	s_mov_b64 s[6:7], 0x8f8da00
	v_lshl_add_u64 v[10:11], v[8:9], 0, s[6:7]
	v_add_co_u32_e32 v8, vcc, s26, v8
	s_lshl_b32 s6, s9, 15
	s_lshl_b32 s7, s8, 17
	v_addc_co_u32_e32 v9, vcc, 0, v9, vcc
	s_or_b32 s6, s6, s7
	flat_load_dwordx4 v[4:7], v[0:1] offset:2560
	s_nop 0
	flat_load_dwordx4 v[0:3], v[2:3] offset:64
	s_nop 0
	flat_load_dwordx2 v[56:57], v[8:9] offset:2560
	flat_load_dwordx2 v[54:55], v[10:11] offset:32
	flat_load_dwordx2 v[50:51], v[10:11] offset:64
	flat_load_dwordx2 v[48:49], v[10:11] offset:96
	s_add_u32 s6, s0, s6
	v_lshlrev_b32_e32 v8, 4, v82
	s_addc_u32 s7, s1, 0
	v_and_b32_e32 v18, 0x70, v8
	v_mov_b32_e32 v19, v137
	v_lshl_add_u64 v[8:9], s[6:7], 0, v[18:19]
	s_mov_b64 s[6:7], 0x980da00
	v_ashrrev_i32_e32 v24, 3, v82
	v_lshl_add_u64 v[20:21], v[8:9], 0, s[6:7]
	s_mov_b64 s[6:7], 0x984da00
	v_ashrrev_i32_e32 v25, 31, v24
	v_lshl_add_u64 v[22:23], v[8:9], 0, s[6:7]
	v_lshlrev_b64 v[8:9], 7, v[24:25]
	v_lshl_add_u64 v[10:11], v[20:21], 0, v[8:9]
	v_lshl_add_u64 v[12:13], v[22:23], 0, v[8:9]
	flat_load_dwordx4 v[8:11], v[10:11]
	s_nop 0
	flat_load_dwordx4 v[12:15], v[12:13]
	v_add_u32_e32 v17, 0x200, v82
	v_ashrrev_i32_e32 v26, 3, v17
	v_add_u32_e32 v18, 16, v18
	v_ashrrev_i32_e32 v27, 31, v26
	v_mad_u64_u32 v[28:29], s[6:7], v24, s47, v[18:19]
	v_lshlrev_b64 v[30:31], 7, v[26:27]
	v_mad_u64_u32 v[24:25], s[6:7], v24, s52, v[18:19]
	v_lshl_add_u64 v[32:33], v[20:21], 0, v[30:31]
	v_lshl_add_u64 v[30:31], v[22:23], 0, v[30:31]
	v_add_u32_e32 v17, 0x400, v82
	v_mov_b32_e32 v132, v28
	v_mov_b32_e32 v133, v24
	flat_load_dwordx4 v[108:111], v[32:33]
	flat_load_dwordx4 v[112:115], v[30:31]
	v_ashrrev_i32_e32 v24, 3, v17
	v_ashrrev_i32_e32 v25, 31, v24
	v_mad_u64_u32 v[28:29], s[6:7], v26, s47, v[18:19]
	v_lshlrev_b64 v[30:31], 7, v[24:25]
	v_mad_u64_u32 v[26:27], s[6:7], v26, s52, v[18:19]
	v_lshl_add_u64 v[32:33], v[20:21], 0, v[30:31]
	v_lshl_add_u64 v[30:31], v[22:23], 0, v[30:31]
	v_add_u32_e32 v17, 0x600, v82
	v_mov_b32_e32 v134, v28
	v_mov_b32_e32 v135, v26
	flat_load_dwordx4 v[116:119], v[32:33]
	flat_load_dwordx4 v[120:123], v[30:31]
	v_ashrrev_i32_e32 v26, 3, v17
	v_ashrrev_i32_e32 v27, 31, v26
	v_mad_u64_u32 v[28:29], s[6:7], v24, s47, v[18:19]
	v_lshlrev_b64 v[30:31], 7, v[26:27]
	v_mad_u64_u32 v[24:25], s[6:7], v24, s52, v[18:19]
	v_lshl_add_u64 v[20:21], v[20:21], 0, v[30:31]
	v_lshl_add_u64 v[22:23], v[22:23], 0, v[30:31]
	v_mul_u32_u24_e32 v17, 0x90, v34
	v_add3_u32 v66, 16, v16, v17
	v_mad_u64_u32 v[16:17], s[6:7], v26, s47, v[18:19]
	v_mad_u64_u32 v[18:19], s[6:7], v26, s52, v[18:19]
	v_mov_b32_e32 v138, v28
	v_mov_b32_e32 v139, v24
	flat_load_dwordx4 v[124:127], v[20:21]
	flat_load_dwordx4 v[128:131], v[22:23]
	s_waitcnt vmcnt(0) lgkmcnt(0)
	s_barrier
	ds_write_b128 v132, v[8:11]
	ds_write_b128 v133, v[12:15] offset:36864
	ds_write_b128 v134, v[108:111]
	ds_write_b128 v135, v[112:115] offset:36864
	ds_write_b128 v138, v[116:119]
	ds_write_b128 v139, v[120:123] offset:36864
	ds_write_b128 v16, v[124:127]
	ds_write_b128 v18, v[128:131] offset:36864
	s_waitcnt lgkmcnt(0)
	s_barrier
	ds_read_b128 v[8:11], v66
	ds_read_b128 v[12:15], v66 offset:64
	ds_read_b128 v[16:19], v66 offset:2304
	ds_read_b128 v[20:23], v66 offset:2368
	ds_read_b128 v[24:27], v66 offset:4608
	ds_read_b128 v[28:31], v66 offset:4672
	ds_read_b128 v[32:35], v66 offset:6912
	ds_read_b128 v[36:39], v66 offset:6976
	s_waitcnt lgkmcnt(7)
	v_mfma_f32_16x16x32_bf16 v[8:11], v[8:11], v[4:7], 0
	s_waitcnt lgkmcnt(5)
	v_mfma_f32_16x16x32_bf16 v[16:19], v[16:19], v[4:7], 0
	s_waitcnt lgkmcnt(3)
	v_mfma_f32_16x16x32_bf16 v[24:27], v[24:27], v[4:7], 0
	s_waitcnt lgkmcnt(1)
	v_mfma_f32_16x16x32_bf16 v[32:35], v[32:35], v[4:7], 0
	v_mfma_f32_16x16x32_bf16 v[58:61], v[12:15], v[0:3], v[8:11]
	v_mfma_f32_16x16x32_bf16 v[62:65], v[20:23], v[0:3], v[16:19]
	v_mfma_f32_16x16x32_bf16 v[68:71], v[28:31], v[0:3], v[24:27]
	s_waitcnt lgkmcnt(0)
	v_mfma_f32_16x16x32_bf16 v[84:87], v[36:39], v[0:3], v[32:35]
	ds_read_b128 v[8:11], v66 offset:9216
	ds_read_b128 v[12:15], v66 offset:9280
	ds_read_b128 v[16:19], v66 offset:11520
	ds_read_b128 v[20:23], v66 offset:11584
	s_waitcnt lgkmcnt(3)
	v_mfma_f32_16x16x32_bf16 v[8:11], v[8:11], v[4:7], 0
	s_waitcnt lgkmcnt(2)
	v_mfma_f32_16x16x32_bf16 v[88:91], v[12:15], v[0:3], v[8:11]
	ds_read_b128 v[12:15], v66 offset:13888
	s_nop 4
	ds_read_b128 v[8:11], v66 offset:13824
	s_waitcnt lgkmcnt(3)
	v_mfma_f32_16x16x32_bf16 v[16:19], v[16:19], v[4:7], 0
	s_waitcnt lgkmcnt(2)
	v_mfma_f32_16x16x32_bf16 v[44:47], v[20:23], v[0:3], v[16:19]
	s_waitcnt lgkmcnt(0)
	v_mfma_f32_16x16x32_bf16 v[8:11], v[8:11], v[4:7], 0
	s_nop 3
	ds_read_b128 v[16:19], v66 offset:16128
	v_mfma_f32_16x16x32_bf16 v[40:43], v[12:15], v[0:3], v[8:11]
	s_nop 2
	ds_read_b128 v[8:11], v66 offset:16192
	s_waitcnt lgkmcnt(1)
	v_mfma_f32_16x16x32_bf16 v[12:15], v[16:19], v[4:7], 0
	s_waitcnt lgkmcnt(0)
	v_mfma_f32_16x16x32_bf16 v[36:39], v[8:11], v[0:3], v[12:15]
	ds_read_b128 v[8:11], v66 offset:18432
	s_nop 4
	ds_read_b128 v[12:15], v66 offset:18496
	ds_read_b128 v[16:19], v66 offset:20736
	ds_read_b128 v[20:23], v66 offset:20800
	s_waitcnt lgkmcnt(3)
	v_mfma_f32_16x16x32_bf16 v[8:11], v[8:11], v[4:7], 0
	s_waitcnt lgkmcnt(2)
	v_mfma_f32_16x16x32_bf16 v[32:35], v[12:15], v[0:3], v[8:11]
	ds_read_b128 v[12:15], v66 offset:23104
	s_nop 4
	ds_read_b128 v[8:11], v66 offset:23040
	s_waitcnt lgkmcnt(3)
	v_mfma_f32_16x16x32_bf16 v[16:19], v[16:19], v[4:7], 0
	s_waitcnt lgkmcnt(2)
	v_mfma_f32_16x16x32_bf16 v[28:31], v[20:23], v[0:3], v[16:19]
	s_waitcnt lgkmcnt(0)
	v_mfma_f32_16x16x32_bf16 v[8:11], v[8:11], v[4:7], 0
	s_nop 3
	ds_read_b128 v[16:19], v66 offset:25344
	v_mfma_f32_16x16x32_bf16 v[24:27], v[12:15], v[0:3], v[8:11]
	s_nop 2
	ds_read_b128 v[8:11], v66 offset:25408
	s_waitcnt lgkmcnt(1)
	v_mfma_f32_16x16x32_bf16 v[12:15], v[16:19], v[4:7], 0
	s_waitcnt lgkmcnt(0)
	v_mfma_f32_16x16x32_bf16 v[16:19], v[8:11], v[0:3], v[12:15]
	ds_read_b128 v[8:11], v66 offset:27648
	s_nop 4
	ds_read_b128 v[12:15], v66 offset:27712
	ds_read_b128 v[20:23], v66 offset:29952
	ds_read_b128 v[72:75], v66 offset:30016
	s_waitcnt lgkmcnt(3)
	v_mfma_f32_16x16x32_bf16 v[8:11], v[8:11], v[4:7], 0
	s_waitcnt lgkmcnt(1)
	v_mfma_f32_16x16x32_bf16 v[76:79], v[20:23], v[4:7], 0
	v_mfma_f32_16x16x32_bf16 v[20:23], v[12:15], v[0:3], v[8:11]
	s_nop 4
	ds_read_b128 v[8:11], v66 offset:32256
	s_waitcnt lgkmcnt(1)
	v_mfma_f32_16x16x32_bf16 v[12:15], v[72:75], v[0:3], v[76:79]
	ds_read_b128 v[72:75], v66 offset:32320
	s_waitcnt lgkmcnt(1)
	v_mfma_f32_16x16x32_bf16 v[8:11], v[8:11], v[4:7], 0
	ds_read_b128 v[76:79], v66 offset:34560
	s_waitcnt lgkmcnt(1)
	v_mfma_f32_16x16x32_bf16 v[8:11], v[72:75], v[0:3], v[8:11]
	ds_read_b128 v[72:75], v66 offset:34624
	s_waitcnt lgkmcnt(1)
	v_mfma_f32_16x16x32_bf16 v[4:7], v[76:79], v[4:7], 0
	s_waitcnt lgkmcnt(0)
	v_mfma_f32_16x16x32_bf16 v[0:3], v[72:75], v[0:3], v[4:7]
	s_nop 5
	v_max3_f32 v4, v58, s54, v59
	v_max3_f32 v4, v4, v60, v61
	v_max3_f32 v4, v4, v62, v63
	v_max3_f32 v4, v4, v64, v65
	v_max3_f32 v4, v4, v68, v69
	v_max3_f32 v4, v4, v70, v71
	v_max3_f32 v4, v4, v84, v85
	v_max3_f32 v4, v4, v86, v87
	v_max3_f32 v4, v4, v88, v89
	v_max3_f32 v4, v4, v90, v91
	v_max3_f32 v4, v4, v44, v45
	v_max3_f32 v4, v4, v46, v47
	v_max3_f32 v4, v4, v40, v41
	v_max3_f32 v4, v4, v42, v43
	v_max3_f32 v4, v4, v36, v37
	v_max3_f32 v4, v4, v38, v39
	v_max3_f32 v4, v4, v32, v33
	v_max3_f32 v4, v4, v34, v35
	v_max3_f32 v4, v4, v28, v29
	v_max3_f32 v4, v4, v30, v31
	v_max3_f32 v4, v4, v24, v25
	v_max3_f32 v4, v4, v26, v27
	v_max3_f32 v4, v4, v16, v17
	v_max3_f32 v4, v4, v18, v19
	v_max3_f32 v4, v4, v20, v21
	v_max3_f32 v4, v4, v22, v23
	v_max3_f32 v4, v4, v12, v13
	v_max3_f32 v4, v4, v14, v15
	v_and_b32_e32 v6, 64, v193
	v_max3_f32 v4, v4, v8, v9
	v_xor_b32_e32 v5, 16, v193
	v_add_u32_e32 v6, 64, v6
	v_max3_f32 v4, v4, v10, v11
	v_cmp_lt_i32_e32 vcc, v5, v6
	v_max3_f32 v4, v4, v0, v1
	v_max3_f32 v4, v4, v2, v3
	v_cndmask_b32_e32 v5, v193, v5, vcc
	v_lshlrev_b32_e32 v92, 2, v5
	ds_bpermute_b32 v5, v92, v4
	s_waitcnt lgkmcnt(0)
	v_max_f32_e32 v5, v5, v5
	v_max_f32_e32 v4, v4, v5
	v_xor_b32_e32 v5, 32, v193
	v_cmp_lt_i32_e32 vcc, v5, v6
	s_nop 1
	v_cndmask_b32_e32 v5, v193, v5, vcc
	v_lshlrev_b32_e32 v93, 2, v5
	ds_bpermute_b32 v5, v93, v4
	s_waitcnt lgkmcnt(0)
	v_max_f32_e32 v5, v5, v5
	v_max_f32_e32 v94, v4, v5
	v_sub_f32_e32 v5, v62, v94
	v_mul_f32_e32 v5, 0x3fb8aa3b, v5
	v_exp_f32_e32 v80, v5
	v_sub_f32_e32 v5, v63, v94
	v_mul_f32_e32 v5, 0x3fb8aa3b, v5
	v_exp_f32_e32 v81, v5
	v_sub_f32_e32 v5, v64, v94
	v_mul_f32_e32 v5, 0x3fb8aa3b, v5
	v_exp_f32_e32 v74, v5
	v_sub_f32_e32 v5, v65, v94
	v_mul_f32_e32 v5, 0x3fb8aa3b, v5
	v_exp_f32_e32 v75, v5
	v_sub_f32_e32 v5, v68, v94
	v_mul_f32_e32 v5, 0x3fb8aa3b, v5
	v_exp_f32_e32 v68, v5
	v_sub_f32_e32 v5, v69, v94
	v_mul_f32_e32 v5, 0x3fb8aa3b, v5
	v_exp_f32_e32 v69, v5
	v_sub_f32_e32 v5, v70, v94
	v_mul_f32_e32 v5, 0x3fb8aa3b, v5
	v_exp_f32_e32 v70, v5
	v_sub_f32_e32 v5, v71, v94
	v_mul_f32_e32 v5, 0x3fb8aa3b, v5
	v_exp_f32_e32 v71, v5
	v_sub_f32_e32 v5, v84, v94
	v_mul_f32_e32 v5, 0x3fb8aa3b, v5
	v_exp_f32_e32 v72, v5
	v_sub_f32_e32 v5, v85, v94
	v_mul_f32_e32 v5, 0x3fb8aa3b, v5
	v_exp_f32_e32 v73, v5
	v_sub_f32_e32 v5, v86, v94
	v_mul_f32_e32 v5, 0x3fb8aa3b, v5
	v_sub_f32_e32 v4, v58, v94
	v_exp_f32_e32 v66, v5
	v_sub_f32_e32 v5, v87, v94
	v_mul_f32_e32 v4, 0x3fb8aa3b, v4
	v_mul_f32_e32 v5, 0x3fb8aa3b, v5
	v_exp_f32_e32 v76, v4
	v_sub_f32_e32 v4, v59, v94
	v_exp_f32_e32 v67, v5
	v_sub_f32_e32 v5, v88, v94
	v_mul_f32_e32 v4, 0x3fb8aa3b, v4
	v_mul_f32_e32 v5, 0x3fb8aa3b, v5
	v_exp_f32_e32 v77, v4
	v_sub_f32_e32 v4, v60, v94
	v_exp_f32_e32 v60, v5
	v_sub_f32_e32 v5, v89, v94
	v_mul_f32_e32 v4, 0x3fb8aa3b, v4
	v_mul_f32_e32 v5, 0x3fb8aa3b, v5
	v_exp_f32_e32 v78, v4
	v_sub_f32_e32 v4, v61, v94
	v_exp_f32_e32 v61, v5
	v_sub_f32_e32 v5, v90, v94
	v_mul_f32_e32 v5, 0x3fb8aa3b, v5
	v_exp_f32_e32 v62, v5
	v_sub_f32_e32 v5, v91, v94
	v_mul_f32_e32 v5, 0x3fb8aa3b, v5
	v_exp_f32_e32 v63, v5
	v_sub_f32_e32 v5, v44, v94
	v_mul_f32_e32 v5, 0x3fb8aa3b, v5
	v_exp_f32_e32 v64, v5
	v_sub_f32_e32 v5, v45, v94
	v_mul_f32_e32 v5, 0x3fb8aa3b, v5
	v_exp_f32_e32 v65, v5
	v_sub_f32_e32 v5, v46, v94
	v_mul_f32_e32 v5, 0x3fb8aa3b, v5
	v_exp_f32_e32 v58, v5
	v_sub_f32_e32 v5, v47, v94
	v_mul_f32_e32 v5, 0x3fb8aa3b, v5
	v_exp_f32_e32 v59, v5
	v_sub_f32_e32 v5, v40, v94
	v_mul_f32_e32 v5, 0x3fb8aa3b, v5
	v_exp_f32_e32 v44, v5
	v_sub_f32_e32 v5, v41, v94
	v_mul_f32_e32 v5, 0x3fb8aa3b, v5
	v_exp_f32_e32 v45, v5
	v_sub_f32_e32 v5, v42, v94
	v_mul_f32_e32 v5, 0x3fb8aa3b, v5
	v_exp_f32_e32 v42, v5
	v_sub_f32_e32 v5, v43, v94
	v_mul_f32_e32 v5, 0x3fb8aa3b, v5
	v_exp_f32_e32 v43, v5
	v_sub_f32_e32 v5, v36, v94
	v_mul_f32_e32 v5, 0x3fb8aa3b, v5
	v_exp_f32_e32 v46, v5
	v_sub_f32_e32 v5, v37, v94
	v_mul_f32_e32 v4, 0x3fb8aa3b, v4
	v_mul_f32_e32 v5, 0x3fb8aa3b, v5
	v_exp_f32_e32 v79, v4
	v_exp_f32_e32 v47, v5
	v_sub_f32_e32 v5, v38, v94
	v_add_f32_e32 v4, 0, v76
	v_mul_f32_e32 v5, 0x3fb8aa3b, v5
	v_add_f32_e32 v4, v77, v4
	v_exp_f32_e32 v40, v5
	v_sub_f32_e32 v5, v39, v94
	v_add_f32_e32 v4, v78, v4
	v_mul_f32_e32 v5, 0x3fb8aa3b, v5
	v_add_f32_e32 v4, v79, v4
	v_exp_f32_e32 v41, v5
	v_sub_f32_e32 v5, v32, v94
	v_add_f32_e32 v4, v80, v4
	v_mul_f32_e32 v5, 0x3fb8aa3b, v5
	v_add_f32_e32 v4, v81, v4
	v_exp_f32_e32 v36, v5
	v_sub_f32_e32 v5, v33, v94
	v_add_f32_e32 v4, v74, v4
	v_mul_f32_e32 v5, 0x3fb8aa3b, v5
	v_add_f32_e32 v4, v75, v4
	v_exp_f32_e32 v37, v5
	v_sub_f32_e32 v5, v34, v94
	v_add_f32_e32 v4, v68, v4
	v_mul_f32_e32 v5, 0x3fb8aa3b, v5
	v_add_f32_e32 v4, v69, v4
	v_exp_f32_e32 v34, v5
	v_sub_f32_e32 v5, v35, v94
	v_add_f32_e32 v4, v70, v4
	v_mul_f32_e32 v5, 0x3fb8aa3b, v5
	v_add_f32_e32 v4, v71, v4
	v_exp_f32_e32 v35, v5
	v_sub_f32_e32 v5, v28, v94
	v_add_f32_e32 v4, v72, v4
	v_mul_f32_e32 v5, 0x3fb8aa3b, v5
	v_add_f32_e32 v4, v73, v4
	v_exp_f32_e32 v38, v5
	v_sub_f32_e32 v5, v29, v94
	v_add_f32_e32 v4, v66, v4
	v_mul_f32_e32 v5, 0x3fb8aa3b, v5
	v_add_f32_e32 v4, v67, v4
	v_exp_f32_e32 v39, v5
	v_sub_f32_e32 v5, v30, v94
	v_add_f32_e32 v4, v60, v4
	v_mul_f32_e32 v5, 0x3fb8aa3b, v5
	v_add_f32_e32 v4, v61, v4
	v_exp_f32_e32 v32, v5
	v_sub_f32_e32 v5, v31, v94
	v_add_f32_e32 v4, v62, v4
	v_mul_f32_e32 v5, 0x3fb8aa3b, v5
	v_add_f32_e32 v4, v63, v4
	v_exp_f32_e32 v33, v5
	v_sub_f32_e32 v5, v24, v94
	v_add_f32_e32 v4, v64, v4
	v_mul_f32_e32 v5, 0x3fb8aa3b, v5
	v_add_f32_e32 v4, v65, v4
	v_exp_f32_e32 v28, v5
	v_sub_f32_e32 v5, v25, v94
	v_add_f32_e32 v4, v58, v4
	v_mul_f32_e32 v5, 0x3fb8aa3b, v5
	v_add_f32_e32 v4, v59, v4
	v_exp_f32_e32 v29, v5
	v_sub_f32_e32 v5, v26, v94
	v_add_f32_e32 v4, v44, v4
	v_mul_f32_e32 v5, 0x3fb8aa3b, v5
	v_add_f32_e32 v4, v45, v4
	v_exp_f32_e32 v26, v5
	v_sub_f32_e32 v5, v27, v94
	v_add_f32_e32 v4, v42, v4
	v_mul_f32_e32 v5, 0x3fb8aa3b, v5
	v_add_f32_e32 v4, v43, v4
	v_exp_f32_e32 v27, v5
	v_sub_f32_e32 v5, v16, v94
	v_add_f32_e32 v4, v46, v4
	v_mul_f32_e32 v5, 0x3fb8aa3b, v5
	v_add_f32_e32 v4, v47, v4
	v_exp_f32_e32 v30, v5
	v_sub_f32_e32 v5, v17, v94
	v_add_f32_e32 v4, v40, v4
	v_mul_f32_e32 v5, 0x3fb8aa3b, v5
	v_add_f32_e32 v4, v41, v4
	v_exp_f32_e32 v31, v5
	v_sub_f32_e32 v5, v18, v94
	v_add_f32_e32 v4, v36, v4
	v_mul_f32_e32 v5, 0x3fb8aa3b, v5
	v_add_f32_e32 v4, v37, v4
	v_exp_f32_e32 v24, v5
	v_sub_f32_e32 v5, v19, v94
	v_add_f32_e32 v4, v34, v4
	v_mul_f32_e32 v5, 0x3fb8aa3b, v5
	v_add_f32_e32 v4, v35, v4
	v_exp_f32_e32 v25, v5
	v_sub_f32_e32 v5, v20, v94
	v_add_f32_e32 v4, v38, v4
	v_mul_f32_e32 v5, 0x3fb8aa3b, v5
	v_add_f32_e32 v4, v39, v4
	v_exp_f32_e32 v16, v5
	v_sub_f32_e32 v5, v21, v94
	v_add_f32_e32 v4, v32, v4
	v_mul_f32_e32 v5, 0x3fb8aa3b, v5
	v_add_f32_e32 v4, v33, v4
	v_exp_f32_e32 v17, v5
	v_sub_f32_e32 v5, v22, v94
	v_add_f32_e32 v4, v28, v4
	v_mul_f32_e32 v5, 0x3fb8aa3b, v5
	v_add_f32_e32 v4, v29, v4
	v_exp_f32_e32 v18, v5
	v_sub_f32_e32 v5, v23, v94
	v_add_f32_e32 v4, v26, v4
	v_mul_f32_e32 v5, 0x3fb8aa3b, v5
	v_add_f32_e32 v4, v27, v4
	v_exp_f32_e32 v19, v5
	v_sub_f32_e32 v5, v12, v94
	v_add_f32_e32 v4, v30, v4
	v_mul_f32_e32 v5, 0x3fb8aa3b, v5
	v_add_f32_e32 v4, v31, v4
	v_exp_f32_e32 v20, v5
	v_sub_f32_e32 v5, v13, v94
	v_add_f32_e32 v4, v24, v4
	v_mul_f32_e32 v5, 0x3fb8aa3b, v5
	v_add_f32_e32 v4, v25, v4
	v_exp_f32_e32 v21, v5
	v_sub_f32_e32 v5, v14, v94
	v_add_f32_e32 v4, v16, v4
	v_mul_f32_e32 v5, 0x3fb8aa3b, v5
	v_add_f32_e32 v4, v17, v4
	v_exp_f32_e32 v12, v5
	v_sub_f32_e32 v5, v15, v94
	v_add_f32_e32 v4, v18, v4
	v_mul_f32_e32 v5, 0x3fb8aa3b, v5
	v_add_f32_e32 v4, v19, v4
	v_exp_f32_e32 v13, v5
	v_add_f32_e32 v4, v20, v4
	v_add_f32_e32 v4, v21, v4
	v_add_f32_e32 v4, v12, v4
	v_add_f32_e32 v14, v13, v4
	v_sub_f32_e32 v4, v8, v94
	v_mul_f32_e32 v4, 0x3fb8aa3b, v4
	v_sub_f32_e32 v5, v9, v94
	v_exp_f32_e32 v4, v4
	v_mul_f32_e32 v5, 0x3fb8aa3b, v5
	v_sub_f32_e32 v6, v10, v94
	v_exp_f32_e32 v5, v5
	v_mul_f32_e32 v6, 0x3fb8aa3b, v6
	v_sub_f32_e32 v7, v11, v94
	v_exp_f32_e32 v6, v6
	v_mul_f32_e32 v7, 0x3fb8aa3b, v7
	v_exp_f32_e32 v7, v7
	v_add_f32_e32 v8, v4, v14
	v_add_f32_e32 v8, v5, v8
	v_sub_f32_e32 v0, v0, v94
	v_add_f32_e32 v8, v6, v8
	v_mul_f32_e32 v0, 0x3fb8aa3b, v0
	v_add_f32_e32 v10, v7, v8
	v_exp_f32_e32 v8, v0
	v_sub_f32_e32 v0, v1, v94
	v_mul_f32_e32 v0, 0x3fb8aa3b, v0
	v_exp_f32_e32 v9, v0
	v_sub_f32_e32 v0, v2, v94
	v_mul_f32_e32 v0, 0x3fb8aa3b, v0
	v_sub_f32_e32 v1, v3, v94
	v_exp_f32_e32 v0, v0
	v_mul_f32_e32 v1, 0x3fb8aa3b, v1
	v_exp_f32_e32 v1, v1
	v_add_f32_e32 v2, v8, v10
	v_add_f32_e32 v2, v9, v2
	v_add_f32_e32 v2, v0, v2
	v_add_f32_e32 v2, v1, v2
	ds_bpermute_b32 v3, v92, v2
	s_waitcnt lgkmcnt(0)
	v_add_f32_e32 v2, v2, v3
	ds_bpermute_b32 v3, v93, v2
	s_waitcnt lgkmcnt(0)
	v_add_f32_e32 v2, v2, v3
	v_div_scale_f32 v3, s[6:7], v2, v2, 1.0
	v_rcp_f32_e32 v10, v3
	s_nop 0
	v_fma_f32 v11, -v3, v10, 1.0
	v_fmac_f32_e32 v10, v11, v10
	v_div_scale_f32 v11, vcc, 1.0, v2, 1.0
	v_mul_f32_e32 v14, v11, v10
	v_fma_f32 v15, -v3, v14, v11
	v_fmac_f32_e32 v14, v15, v10
	v_fma_f32 v3, -v3, v14, v11
	v_div_fmas_f32 v3, v3, v10, v14
	v_div_fixup_f32 v2, v3, v2, 1.0
	v_bfe_u32 v3, v82, 2, 2
	v_lshl_or_b32 v3, v83, 2, v3
	v_mul_u32_u24_e32 v3, 0xa0, v3
	v_lshlrev_b32_e32 v10, 3, v82
	v_and_b32_e32 v10, 24, v10
	v_pk_mul_f32 v[14:15], v[76:77], v[2:3] op_sel_hi:[1,0]
	v_add3_u32 v10, 16, v3, v10
	v_cvt_pk_bf16_f32 v76, v14, v15
	v_pk_mul_f32 v[14:15], v[78:79], v[2:3] op_sel_hi:[1,0]
	s_nop 0
	v_cvt_pk_bf16_f32 v77, v14, v15
	v_pk_mul_f32 v[14:15], v[80:81], v[2:3] op_sel_hi:[1,0]
	ds_read_b64_tr_b16 v[82:83], v10 offset:39424
	ds_read_b64_tr_b16 v[80:81], v10 offset:36864
	ds_read_b64_tr_b16 v[86:87], v10 offset:39456
	ds_read_b64_tr_b16 v[84:85], v10 offset:36896
	ds_read_b64_tr_b16 v[88:89], v10 offset:36928
	ds_read_b64_tr_b16 v[92:93], v10 offset:36960
	ds_read_b64_tr_b16 v[90:91], v10 offset:39488
	ds_read_b64_tr_b16 v[94:95], v10 offset:39520
	v_cvt_pk_bf16_f32 v78, v14, v15
	v_pk_mul_f32 v[14:15], v[74:75], v[2:3] op_sel_hi:[1,0]
	v_add_u32_e32 v3, 0x9000, v10
	v_cvt_pk_bf16_f32 v79, v14, v15
	s_waitcnt lgkmcnt(6)
	s_nop 0
	v_mfma_f32_16x16x32_bf16 v[80:83], v[80:83], v[76:79], 0
	s_waitcnt lgkmcnt(4)
	v_mfma_f32_16x16x32_bf16 v[84:87], v[84:87], v[76:79], 0
	s_waitcnt lgkmcnt(1)
	v_mfma_f32_16x16x32_bf16 v[88:91], v[88:91], v[76:79], 0
	s_waitcnt lgkmcnt(0)
	v_mfma_f32_16x16x32_bf16 v[74:77], v[92:95], v[76:79], 0
	v_mul_f32_e64 v14, v68, v2
	v_mul_f32_e64 v15, v69, v2
	ds_read_b64_tr_b16 v[94:95], v10 offset:44544
	ds_read_b64_tr_b16 v[92:93], v10 offset:41984
	ds_read_b64_tr_b16 v[98:99], v10 offset:44576
	ds_read_b64_tr_b16 v[96:97], v10 offset:42016
	ds_read_b64_tr_b16 v[100:101], v10 offset:42048
	ds_read_b64_tr_b16 v[104:105], v10 offset:42080
	ds_read_b64_tr_b16 v[102:103], v10 offset:44608
	ds_read_b64_tr_b16 v[106:107], v10 offset:44640
	v_cvt_pk_bf16_f32 v68, v14, v15
	v_pk_mul_f32 v[14:15], v[70:71], v[2:3] op_sel_hi:[1,0]
	s_nop 0
	v_cvt_pk_bf16_f32 v69, v14, v15
	v_pk_mul_f32 v[14:15], v[72:73], v[2:3] op_sel_hi:[1,0]
	s_nop 0
	v_cvt_pk_bf16_f32 v70, v14, v15
	v_pk_mul_f32 v[14:15], v[66:67], v[2:3] op_sel_hi:[1,0]
	s_nop 0
	v_cvt_pk_bf16_f32 v71, v14, v15
	s_waitcnt lgkmcnt(6)
	s_nop 0
	v_mfma_f32_16x16x32_bf16 v[78:81], v[92:95], v[68:71], v[80:83]
	s_waitcnt lgkmcnt(4)
	v_mfma_f32_16x16x32_bf16 v[82:85], v[96:99], v[68:71], v[84:87]
	s_waitcnt lgkmcnt(1)
	v_mfma_f32_16x16x32_bf16 v[86:89], v[100:103], v[68:71], v[88:91]
	s_waitcnt lgkmcnt(0)
	v_mfma_f32_16x16x32_bf16 v[66:69], v[104:107], v[68:71], v[74:77]
	v_mul_f32_e64 v14, v60, v2
	v_mul_f32_e64 v15, v61, v2
	ds_read_b64_tr_b16 v[72:73], v10 offset:49664
	ds_read_b64_tr_b16 v[70:71], v10 offset:47104
	ds_read_b64_tr_b16 v[76:77], v10 offset:49696
	ds_read_b64_tr_b16 v[74:75], v10 offset:47136
	ds_read_b64_tr_b16 v[90:91], v10 offset:47168
	ds_read_b64_tr_b16 v[94:95], v10 offset:47200
	ds_read_b64_tr_b16 v[92:93], v10 offset:49728
	ds_read_b64_tr_b16 v[96:97], v10 offset:49760
	v_cvt_pk_bf16_f32 v60, v14, v15
	v_pk_mul_f32 v[14:15], v[62:63], v[2:3] op_sel_hi:[1,0]
	s_nop 0
	v_cvt_pk_bf16_f32 v61, v14, v15
	v_pk_mul_f32 v[14:15], v[64:65], v[2:3] op_sel_hi:[1,0]
	s_nop 0
	v_cvt_pk_bf16_f32 v62, v14, v15
	v_pk_mul_f32 v[14:15], v[58:59], v[2:3] op_sel_hi:[1,0]
	s_nop 0
	v_cvt_pk_bf16_f32 v63, v14, v15
	s_waitcnt lgkmcnt(6)
	s_nop 0
	v_mfma_f32_16x16x32_bf16 v[70:73], v[70:73], v[60:63], v[78:81]
	s_waitcnt lgkmcnt(4)
	v_mfma_f32_16x16x32_bf16 v[74:77], v[74:77], v[60:63], v[82:85]
	s_waitcnt lgkmcnt(1)
	v_mfma_f32_16x16x32_bf16 v[78:81], v[90:93], v[60:63], v[86:89]
	s_waitcnt lgkmcnt(0)
	v_mfma_f32_16x16x32_bf16 v[58:61], v[94:97], v[60:63], v[66:69]
	v_mul_f32_e64 v14, v44, v2
	v_mul_f32_e64 v15, v45, v2
	ds_read_b64_tr_b16 v[64:65], v10 offset:54784
	ds_read_b64_tr_b16 v[62:63], v10 offset:52224
	v_cvt_pk_bf16_f32 v44, v14, v15
	v_pk_mul_f32 v[14:15], v[42:43], v[2:3] op_sel_hi:[1,0]
	s_nop 0
	v_cvt_pk_bf16_f32 v45, v14, v15
	v_pk_mul_f32 v[14:15], v[46:47], v[2:3] op_sel_hi:[1,0]
	s_nop 0
	v_cvt_pk_bf16_f32 v46, v14, v15
	v_pk_mul_f32 v[14:15], v[40:41], v[2:3] op_sel_hi:[1,0]
	ds_read_b64_tr_b16 v[42:43], v10 offset:54816
	ds_read_b64_tr_b16 v[40:41], v10 offset:52256
	ds_read_b64_tr_b16 v[66:67], v10 offset:52288
	ds_read_b64_tr_b16 v[82:83], v10 offset:52320
	ds_read_b64_tr_b16 v[68:69], v10 offset:54848
	ds_read_b64_tr_b16 v[84:85], v10 offset:54880
	v_cvt_pk_bf16_f32 v47, v14, v15
	s_waitcnt lgkmcnt(6)
	s_nop 0
	v_mfma_f32_16x16x32_bf16 v[62:65], v[62:65], v[44:47], v[70:73]
	s_waitcnt lgkmcnt(4)
	v_mfma_f32_16x16x32_bf16 v[40:43], v[40:43], v[44:47], v[74:77]
	s_waitcnt lgkmcnt(1)
	v_mfma_f32_16x16x32_bf16 v[66:69], v[66:69], v[44:47], v[78:81]
	s_waitcnt lgkmcnt(0)
	v_mfma_f32_16x16x32_bf16 v[44:47], v[82:85], v[44:47], v[58:61]
	v_mul_f32_e64 v14, v36, v2
	v_mul_f32_e64 v15, v37, v2
	s_nop 0
	ds_read_b64_tr_b16 v[60:61], v10 offset:59904
	ds_read_b64_tr_b16 v[58:59], v10 offset:57344
	v_cvt_pk_bf16_f32 v36, v14, v15
	v_pk_mul_f32 v[14:15], v[34:35], v[2:3] op_sel_hi:[1,0]
	s_nop 0
	v_cvt_pk_bf16_f32 v37, v14, v15
	v_pk_mul_f32 v[14:15], v[38:39], v[2:3] op_sel_hi:[1,0]
	s_nop 0
	v_cvt_pk_bf16_f32 v38, v14, v15
	v_pk_mul_f32 v[14:15], v[32:33], v[2:3] op_sel_hi:[1,0]
	ds_read_b64_tr_b16 v[34:35], v10 offset:59936
	ds_read_b64_tr_b16 v[32:33], v10 offset:57376
	ds_read_b64_tr_b16 v[70:71], v10 offset:57408
	ds_read_b64_tr_b16 v[74:75], v10 offset:57440
	ds_read_b64_tr_b16 v[72:73], v10 offset:59968
	ds_read_b64_tr_b16 v[76:77], v10 offset:60000
	v_cvt_pk_bf16_f32 v39, v14, v15
	s_waitcnt lgkmcnt(6)
	s_nop 0
	v_mfma_f32_16x16x32_bf16 v[58:61], v[58:61], v[36:39], v[62:65]
	s_waitcnt lgkmcnt(4)
	v_mfma_f32_16x16x32_bf16 v[32:35], v[32:35], v[36:39], v[40:43]
	s_waitcnt lgkmcnt(1)
	v_mfma_f32_16x16x32_bf16 v[40:43], v[70:73], v[36:39], v[66:69]
	s_waitcnt lgkmcnt(0)
	v_mfma_f32_16x16x32_bf16 v[36:39], v[74:77], v[36:39], v[44:47]
	v_mul_f32_e64 v14, v28, v2
	v_mul_f32_e64 v15, v29, v2
	s_nop 0
	ds_read_b64_tr_b16 v[46:47], v10 offset:65024
	ds_read_b64_tr_b16 v[44:45], v10 offset:62464
	v_cvt_pk_bf16_f32 v28, v14, v15
	v_pk_mul_f32 v[14:15], v[26:27], v[2:3] op_sel_hi:[1,0]
	s_nop 0
	v_cvt_pk_bf16_f32 v29, v14, v15
	v_pk_mul_f32 v[14:15], v[30:31], v[2:3] op_sel_hi:[1,0]
	s_nop 0
	v_cvt_pk_bf16_f32 v30, v14, v15
	v_pk_mul_f32 v[14:15], v[24:25], v[2:3] op_sel_hi:[1,0]
	ds_read_b64_tr_b16 v[24:25], v10 offset:65056
	ds_read_b64_tr_b16 v[22:23], v10 offset:62496
	ds_read_b64_tr_b16 v[62:63], v10 offset:62528
	ds_read_b64_tr_b16 v[66:67], v10 offset:62560
	ds_read_b64_tr_b16 v[64:65], v10 offset:65088
	ds_read_b64_tr_b16 v[68:69], v10 offset:65120
	v_cvt_pk_bf16_f32 v31, v14, v15
	s_waitcnt lgkmcnt(6)
	s_nop 0
	v_mfma_f32_16x16x32_bf16 v[44:47], v[44:47], v[28:31], v[58:61]
	s_waitcnt lgkmcnt(4)
	v_mfma_f32_16x16x32_bf16 v[22:25], v[22:25], v[28:31], v[32:35]
	s_waitcnt lgkmcnt(1)
	v_mfma_f32_16x16x32_bf16 v[32:35], v[62:65], v[28:31], v[40:43]
	s_waitcnt lgkmcnt(0)
	v_mfma_f32_16x16x32_bf16 v[26:29], v[66:69], v[28:31], v[36:39]
	v_mul_f32_e64 v10, v16, v2
	v_mul_f32_e64 v11, v17, v2
	v_cvt_pk_bf16_f32 v14, v10, v11
	v_pk_mul_f32 v[10:11], v[18:19], v[2:3] op_sel_hi:[1,0]
	s_nop 0
	v_cvt_pk_bf16_f32 v15, v10, v11
	v_pk_mul_f32 v[10:11], v[20:21], v[2:3] op_sel_hi:[1,0]
	ds_read_b64_tr_b16 v[20:21], v3 offset:33280
	ds_read_b64_tr_b16 v[18:19], v3 offset:30720
	v_cvt_pk_bf16_f32 v16, v10, v11
	v_pk_mul_f32 v[10:11], v[12:13], v[2:3] op_sel_hi:[1,0]
	s_nop 0
	v_cvt_pk_bf16_f32 v17, v10, v11
	ds_read_b64_tr_b16 v[12:13], v3 offset:33312
	ds_read_b64_tr_b16 v[10:11], v3 offset:30752
	ds_read_b64_tr_b16 v[36:37], v3 offset:30784
	ds_read_b64_tr_b16 v[40:41], v3 offset:30816
	ds_read_b64_tr_b16 v[38:39], v3 offset:33344
	ds_read_b64_tr_b16 v[42:43], v3 offset:33376
	s_waitcnt lgkmcnt(6)
	v_mfma_f32_16x16x32_bf16 v[18:21], v[18:21], v[14:17], v[44:47]
	s_waitcnt lgkmcnt(4)
	v_mfma_f32_16x16x32_bf16 v[10:13], v[10:13], v[14:17], v[22:25]
	s_waitcnt lgkmcnt(1)
	v_mfma_f32_16x16x32_bf16 v[22:25], v[36:39], v[14:17], v[32:35]
	s_waitcnt lgkmcnt(0)
	v_mfma_f32_16x16x32_bf16 v[14:17], v[40:43], v[14:17], v[26:29]
	v_mul_f32_e64 v4, v4, v2
	v_mul_f32_e64 v5, v5, v2
	v_pk_mul_f32 v[6:7], v[6:7], v[2:3] op_sel_hi:[1,0]
	v_cvt_pk_bf16_f32 v4, v4, v5
	v_cvt_pk_bf16_f32 v5, v6, v7
	v_pk_mul_f32 v[6:7], v[8:9], v[2:3] op_sel_hi:[1,0]
	v_pk_mul_f32 v[0:1], v[0:1], v[2:3] op_sel_hi:[1,0]
	v_cvt_pk_bf16_f32 v6, v6, v7
	ds_read_b64_tr_b16 v[28:29], v3 offset:38400
	ds_read_b64_tr_b16 v[26:27], v3 offset:35840
	v_cvt_pk_bf16_f32 v7, v0, v1
	ds_read_b64_tr_b16 v[32:33], v3 offset:38432
	ds_read_b64_tr_b16 v[30:31], v3 offset:35872
	ds_read_b64_tr_b16 v[34:35], v3 offset:35904
	ds_read_b64_tr_b16 v[0:1], v3 offset:35936
	ds_read_b64_tr_b16 v[36:37], v3 offset:38464
	ds_read_b64_tr_b16 v[2:3], v3 offset:38496
	s_waitcnt lgkmcnt(6)
	v_mfma_f32_16x16x32_bf16 v[18:21], v[26:29], v[4:7], v[18:21]
	s_waitcnt lgkmcnt(4)
	v_mfma_f32_16x16x32_bf16 v[8:11], v[30:33], v[4:7], v[10:13]
	s_waitcnt lgkmcnt(1)
	v_mfma_f32_16x16x32_bf16 v[22:25], v[34:37], v[4:7], v[22:25]
	s_waitcnt lgkmcnt(0)
	v_mfma_f32_16x16x32_bf16 v[0:3], v[0:3], v[4:7], v[14:17]
	v_lshl_add_u64 v[4:5], v[52:53], 0, s[96:97]
	v_lshlrev_b64 v[4:5], 11, v[4:5]
	v_lshl_add_u64 v[4:5], s[0:1], 0, v[4:5]
	v_lshl_add_u64 v[4:5], v[4:5], 0, s[4:5]
	v_lshlrev_b32_e32 v12, 16, v56
	v_and_b32_e32 v13, 0xffff0000, v56
	v_lshl_add_u64 v[4:5], v[4:5], 0, v[136:137]
	s_mov_b64 s[0:1], 0xa5b4000
	v_mul_f32_e32 v12, v18, v12
	v_mul_f32_e32 v13, v19, v13
	v_lshl_add_u64 v[6:7], v[4:5], 0, s[0:1]
	v_cvt_pk_bf16_f32 v12, v12, v13
	v_lshlrev_b32_e32 v13, 16, v57
	v_and_b32_e32 v14, 0xffff0000, v57
	s_mov_b32 s0, 0xa5b4000
	v_mul_f32_e32 v13, v20, v13
	v_mul_f32_e32 v14, v21, v14
	v_add_co_u32_e32 v4, vcc, s0, v4
	v_cvt_pk_bf16_f32 v13, v13, v14
	s_nop 0
	v_addc_co_u32_e32 v5, vcc, 0, v5, vcc
	flat_store_dwordx2 v[4:5], v[12:13]
	v_lshlrev_b32_e32 v4, 16, v54
	v_and_b32_e32 v5, 0xffff0000, v54
	v_mul_f32_e32 v4, v8, v4
	v_mul_f32_e32 v5, v9, v5
	v_cvt_pk_bf16_f32 v4, v4, v5
	v_lshlrev_b32_e32 v5, 16, v55
	v_and_b32_e32 v8, 0xffff0000, v55
	v_mul_f32_e32 v5, v10, v5
	v_mul_f32_e32 v8, v11, v8
	v_cvt_pk_bf16_f32 v5, v5, v8
	flat_store_dwordx2 v[6:7], v[4:5] offset:32
	v_lshlrev_b32_e32 v4, 16, v50
	v_and_b32_e32 v5, 0xffff0000, v50
	v_mul_f32_e32 v4, v22, v4
	v_mul_f32_e32 v5, v23, v5
	v_cvt_pk_bf16_f32 v4, v4, v5
	v_lshlrev_b32_e32 v5, 16, v51
	v_and_b32_e32 v8, 0xffff0000, v51
	v_mul_f32_e32 v5, v24, v5
	v_mul_f32_e32 v8, v25, v8
	v_cvt_pk_bf16_f32 v5, v5, v8
	flat_store_dwordx2 v[6:7], v[4:5] offset:64
	v_lshlrev_b32_e32 v4, 16, v48
	v_mul_f32_e32 v0, v0, v4
	v_and_b32_e32 v4, 0xffff0000, v48
	v_mul_f32_e32 v1, v1, v4
	v_cvt_pk_bf16_f32 v0, v0, v1
	v_lshlrev_b32_e32 v1, 16, v49
	v_mul_f32_e32 v1, v2, v1
	v_and_b32_e32 v2, 0xffff0000, v49
	v_mul_f32_e32 v2, v3, v2
	v_cvt_pk_bf16_f32 v1, v1, v2
	flat_store_dwordx2 v[6:7], v[0:1] offset:96

.LBB0_1037:
	s_andn2_b64 vcc, exec, s[0:1]
	s_cbranch_vccnz .LBB0_408
	s_mul_hi_i32 s4, s56, 0x2aaaaaab
	s_lshr_b32 s5, s4, 31
	s_ashr_i32 s4, s4, 6
	s_add_i32 s6, s4, s5
	s_ashr_i32 s4, s56, 6
	s_mul_hi_i32 s5, s4, 0x2aaaaaab
	s_lshr_b32 s7, s5, 31
	s_add_i32 s5, s5, s7
	s_mul_i32 s5, s5, 6
	s_sub_i32 s4, s4, s5
	s_and_b32 s5, s4, -2
	s_lshr_b32 s7, 64, s5
	s_and_b32 s12, s56, 63
	s_add_i32 s7, s7, -1
	s_and_b32 s14, s7, s12
	s_mul_i32 s7, s6, 6
	s_add_i32 s8, s7, s4
	s_ashr_i32 s9, s8, 31
	s_mov_b64 s[0:1], s[38:39]
	v_mov_b32_e32 v69, v192
	s_lshl_b32 s7, s12, 7
	s_lshl_b64 s[8:9], s[8:9], 20
	s_add_u32 s10, s0, s8
	v_ashrrev_i32_e32 v0, 2, v69
	s_addc_u32 s11, s1, s9
	s_lshl_b32 s8, s12, 14
	v_bfi_b32 v32, -16, v0, v69
	s_add_u32 s12, s10, s8
	v_ashrrev_i32_e32 v33, 31, v32
	v_bfe_u32 v68, v69, 4, 2
	s_addc_u32 s13, s11, 0
	v_lshlrev_b64 v[0:1], 7, v[32:33]
	s_add_i32 s16, s7, 0xffffff80
	v_lshl_add_u64 v[0:1], s[12:13], 0, v[0:1]
	v_lshlrev_b32_e32 v16, 4, v68
	v_mov_b32_e32 v17, v137
	s_cmp_lg_u32 s14, 0
	v_lshl_add_u64 v[0:1], v[0:1], 0, v[16:17]
	s_mov_b64 s[12:13], 0x544da00
	s_cselect_b64 s[8:9], -1, 0
	s_waitcnt lgkmcnt(0)
	v_lshl_add_u64 v[2:3], v[0:1], 0, s[12:13]
	s_mov_b32 s12, 0x544d000
	v_lshlrev_b32_e32 v8, 4, v69
	s_and_b64 s[14:15], s[8:9], exec
	v_add_co_u32_e32 v0, vcc, s12, v0
	v_and_b32_e32 v18, 0x70, v8
	v_mov_b32_e32 v19, v137
	s_cselect_b32 s14, s16, s7
	v_addc_co_u32_e32 v1, vcc, 0, v1, vcc
	v_lshl_add_u64 v[8:9], s[10:11], 0, v[18:19]
	s_mov_b64 s[10:11], 0x604da00
	v_ashrrev_i32_e32 v17, 3, v69
	v_lshl_add_u64 v[20:21], v[8:9], 0, s[10:11]
	s_mov_b64 s[10:11], 0x6c4da00
	v_mov_b32_e32 v19, s16
	v_mov_b32_e32 v33, s14
	v_cmp_gt_i32_e32 vcc, s48, v17
	v_lshl_add_u64 v[22:23], v[8:9], 0, s[10:11]
	flat_load_dwordx4 v[4:7], v[0:1] offset:2560
	s_nop 0
	flat_load_dwordx4 v[0:3], v[2:3] offset:64
	v_cndmask_b32_e32 v8, v19, v33, vcc
	v_add_u32_e32 v8, v8, v17
	v_ashrrev_i32_e32 v9, 31, v8
	v_lshlrev_b64 v[8:9], 7, v[8:9]
	v_lshl_add_u64 v[10:11], v[20:21], 0, v[8:9]
	v_lshl_add_u64 v[12:13], v[22:23], 0, v[8:9]
	flat_load_dwordx4 v[8:11], v[10:11]
	s_nop 0
	flat_load_dwordx4 v[12:15], v[12:13]
	v_add_u32_e32 v24, 0x200, v69
	v_ashrrev_i32_e32 v34, 3, v24
	v_add_u32_e32 v18, 16, v18
	v_cmp_gt_i32_e32 vcc, s48, v34
	v_mad_u64_u32 v[24:25], s[10:11], v17, s47, v[18:19]
	v_mad_u64_u32 v[26:27], s[10:11], v17, s52, v[18:19]
	v_cndmask_b32_e32 v17, v19, v33, vcc
	v_add_u32_e32 v28, v17, v34
	v_ashrrev_i32_e32 v29, 31, v28
	v_lshlrev_b64 v[28:29], 7, v[28:29]
	v_lshl_add_u64 v[30:31], v[20:21], 0, v[28:29]
	v_lshl_add_u64 v[28:29], v[22:23], 0, v[28:29]
	v_add_u32_e32 v17, 0x400, v69
	v_ashrrev_i32_e32 v17, 3, v17
	v_cmp_gt_i32_e32 vcc, s48, v17
	v_lshlrev_b32_e32 v136, 3, v68
	v_mov_b32_e32 v132, v24
	v_mov_b32_e32 v133, v26
	flat_load_dwordx4 v[108:111], v[30:31]
	flat_load_dwordx4 v[112:115], v[28:29]
	v_mad_u64_u32 v[24:25], s[10:11], v34, s47, v[18:19]
	v_cndmask_b32_e32 v25, v19, v33, vcc
	v_add_u32_e32 v28, v25, v17
	v_ashrrev_i32_e32 v29, 31, v28
	v_lshlrev_b64 v[28:29], 7, v[28:29]
	v_mad_u64_u32 v[26:27], s[10:11], v34, s52, v[18:19]
	v_lshl_add_u64 v[30:31], v[20:21], 0, v[28:29]
	v_lshl_add_u64 v[28:29], v[22:23], 0, v[28:29]
	v_mov_b32_e32 v134, v24
	v_mov_b32_e32 v135, v26
	flat_load_dwordx4 v[116:119], v[30:31]
	flat_load_dwordx4 v[120:123], v[28:29]
	v_add_u32_e32 v24, 0x600, v69
	v_ashrrev_i32_e32 v30, 3, v24
	v_cmp_gt_i32_e32 vcc, s48, v30
	v_mad_u64_u32 v[24:25], s[10:11], v17, s47, v[18:19]
	v_mad_u64_u32 v[26:27], s[10:11], v17, s52, v[18:19]
	v_cndmask_b32_e32 v17, v19, v33, vcc
	v_add_u32_e32 v28, v17, v30
	v_ashrrev_i32_e32 v29, 31, v28
	v_lshlrev_b64 v[28:29], 7, v[28:29]
	v_lshl_add_u64 v[20:21], v[20:21], 0, v[28:29]
	v_lshl_add_u64 v[22:23], v[22:23], 0, v[28:29]
	v_and_b32_e32 v17, 15, v69
	v_mul_u32_u24_e32 v17, 0x90, v17
	v_add3_u32 v33, 16, v16, v17
	v_mad_u64_u32 v[16:17], s[10:11], v30, s47, v[18:19]
	v_mad_u64_u32 v[18:19], s[10:11], v30, s52, v[18:19]
	v_mov_b32_e32 v138, v24
	v_mov_b32_e32 v139, v26
	flat_load_dwordx4 v[124:127], v[20:21]
	flat_load_dwordx4 v[128:131], v[22:23]
	s_waitcnt vmcnt(0) lgkmcnt(0)
	s_barrier
	ds_write_b128 v132, v[8:11]
	ds_write_b128 v133, v[12:15] offset:36864
	ds_write_b128 v134, v[108:111]
	ds_write_b128 v135, v[112:115] offset:36864
	ds_write_b128 v138, v[116:119]
	ds_write_b128 v139, v[120:123] offset:36864
	ds_write_b128 v16, v[124:127]
	ds_write_b128 v18, v[128:131] offset:36864
	s_waitcnt lgkmcnt(0)
	s_barrier
	ds_read_b128 v[8:11], v33
	ds_read_b128 v[12:15], v33 offset:64
	ds_read_b128 v[16:19], v33 offset:2304
	ds_read_b128 v[20:23], v33 offset:2368
	ds_read_b128 v[24:27], v33 offset:4608
	ds_read_b128 v[28:31], v33 offset:4672
	ds_read_b128 v[34:37], v33 offset:6912
	ds_read_b128 v[38:41], v33 offset:6976
	s_waitcnt lgkmcnt(7)
	v_mfma_f32_16x16x32_bf16 v[8:11], v[8:11], v[4:7], 0
	s_waitcnt lgkmcnt(5)
	v_mfma_f32_16x16x32_bf16 v[16:19], v[16:19], v[4:7], 0
	s_waitcnt lgkmcnt(3)
	v_mfma_f32_16x16x32_bf16 v[24:27], v[24:27], v[4:7], 0
	s_waitcnt lgkmcnt(1)
	v_mfma_f32_16x16x32_bf16 v[34:37], v[34:37], v[4:7], 0
	v_mfma_f32_16x16x32_bf16 v[42:45], v[12:15], v[0:3], v[8:11]
	v_mfma_f32_16x16x32_bf16 v[46:49], v[20:23], v[0:3], v[16:19]
	v_mfma_f32_16x16x32_bf16 v[50:53], v[28:31], v[0:3], v[24:27]
	s_waitcnt lgkmcnt(0)
	v_mfma_f32_16x16x32_bf16 v[34:37], v[38:41], v[0:3], v[34:37]
	ds_read_b128 v[8:11], v33 offset:9216
	ds_read_b128 v[12:15], v33 offset:9280
	ds_read_b128 v[16:19], v33 offset:11520
	ds_read_b128 v[20:23], v33 offset:11584
	s_waitcnt lgkmcnt(3)
	v_mfma_f32_16x16x32_bf16 v[8:11], v[8:11], v[4:7], 0
	s_waitcnt lgkmcnt(2)
	v_mfma_f32_16x16x32_bf16 v[38:41], v[12:15], v[0:3], v[8:11]
	ds_read_b128 v[12:15], v33 offset:13888
	s_nop 4
	ds_read_b128 v[8:11], v33 offset:13824
	s_waitcnt lgkmcnt(3)
	v_mfma_f32_16x16x32_bf16 v[16:19], v[16:19], v[4:7], 0
	s_waitcnt lgkmcnt(2)
	v_mfma_f32_16x16x32_bf16 v[54:57], v[20:23], v[0:3], v[16:19]
	s_waitcnt lgkmcnt(0)
	v_mfma_f32_16x16x32_bf16 v[8:11], v[8:11], v[4:7], 0
	s_nop 3
	ds_read_b128 v[16:19], v33 offset:16128
	v_mfma_f32_16x16x32_bf16 v[58:61], v[12:15], v[0:3], v[8:11]
	s_nop 2
	ds_read_b128 v[8:11], v33 offset:16192
	s_waitcnt lgkmcnt(1)
	v_mfma_f32_16x16x32_bf16 v[12:15], v[16:19], v[4:7], 0
	s_waitcnt lgkmcnt(0)
	v_mfma_f32_16x16x32_bf16 v[62:65], v[8:11], v[0:3], v[12:15]
	ds_read_b128 v[8:11], v33 offset:18432
	s_nop 4
	ds_read_b128 v[12:15], v33 offset:18496
	ds_read_b128 v[16:19], v33 offset:20736
	ds_read_b128 v[20:23], v33 offset:20800
	s_waitcnt lgkmcnt(3)
	v_mfma_f32_16x16x32_bf16 v[8:11], v[8:11], v[4:7], 0
	s_waitcnt lgkmcnt(2)
	v_mfma_f32_16x16x32_bf16 v[72:75], v[12:15], v[0:3], v[8:11]
	ds_read_b128 v[12:15], v33 offset:23104
	s_nop 4
	ds_read_b128 v[8:11], v33 offset:23040
	s_waitcnt lgkmcnt(3)
	v_mfma_f32_16x16x32_bf16 v[16:19], v[16:19], v[4:7], 0
	s_waitcnt lgkmcnt(2)
	v_mfma_f32_16x16x32_bf16 v[16:19], v[20:23], v[0:3], v[16:19]
	ds_read_b128 v[20:23], v33 offset:25344
	s_waitcnt lgkmcnt(1)
	v_mfma_f32_16x16x32_bf16 v[8:11], v[8:11], v[4:7], 0
	v_mfma_f32_16x16x32_bf16 v[12:15], v[12:15], v[0:3], v[8:11]
	s_nop 6
	ds_read_b128 v[8:11], v33 offset:25408
	s_waitcnt lgkmcnt(1)
	v_mfma_f32_16x16x32_bf16 v[20:23], v[20:23], v[4:7], 0
	s_waitcnt lgkmcnt(0)
	v_mfma_f32_16x16x32_bf16 v[8:11], v[8:11], v[0:3], v[20:23]
	s_nop 5
	ds_read_b128 v[20:23], v33 offset:27648
	ds_read_b128 v[24:27], v33 offset:27712
	ds_read_b128 v[28:31], v33 offset:29952
	ds_read_b128 v[76:79], v33 offset:30016
	s_waitcnt lgkmcnt(3)
	v_mfma_f32_16x16x32_bf16 v[20:23], v[20:23], v[4:7], 0
	s_waitcnt lgkmcnt(1)
	v_mfma_f32_16x16x32_bf16 v[80:83], v[28:31], v[4:7], 0
	v_mfma_f32_16x16x32_bf16 v[28:31], v[24:27], v[0:3], v[20:23]
	ds_read_b128 v[24:27], v33 offset:32256
	s_waitcnt lgkmcnt(1)
	v_mfma_f32_16x16x32_bf16 v[20:23], v[76:79], v[0:3], v[80:83]
	ds_read_b128 v[76:79], v33 offset:32320
	s_waitcnt lgkmcnt(1)
	v_mfma_f32_16x16x32_bf16 v[24:27], v[24:27], v[4:7], 0
	s_nop 0
	ds_read_b128 v[80:83], v33 offset:34560
	s_waitcnt lgkmcnt(1)
	v_mfma_f32_16x16x32_bf16 v[24:27], v[76:79], v[0:3], v[24:27]
	ds_read_b128 v[76:79], v33 offset:34624
	s_waitcnt lgkmcnt(1)
	v_mfma_f32_16x16x32_bf16 v[4:7], v[80:83], v[4:7], 0
	s_waitcnt lgkmcnt(0)
	v_mfma_f32_16x16x32_bf16 v[0:3], v[76:79], v[0:3], v[4:7]
	v_lshlrev_b32_e32 v70, 2, v68
	v_cmp_ge_i32_e32 vcc, v70, v32
	s_nop 3
	v_mov_b32_e32 v4, s50
	s_and_b64 vcc, s[8:9], vcc
	v_cndmask_b32_e32 v5, v4, v42, vcc
	v_or_b32_e32 v4, 1, v70
	v_cmp_ge_i32_e32 vcc, v4, v32
	s_and_b64 vcc, s[8:9], vcc
	v_or_b32_e32 v7, 2, v70
	v_cndmask_b32_e32 v6, v215, v43, vcc
	v_cmp_ge_i32_e32 vcc, v7, v32
	s_and_b64 vcc, s[8:9], vcc
	v_or_b32_e32 v42, 3, v70
	v_cndmask_b32_e32 v33, v215, v44, vcc
	v_cmp_ge_i32_e32 vcc, v42, v32
	s_and_b64 vcc, s[8:9], vcc
	v_max3_f32 v4, v5, s54, v6
	v_cndmask_b32_e32 v43, v215, v45, vcc
	v_or_b32_e32 v45, 16, v70
	v_cmp_ge_i32_e32 vcc, v45, v32
	v_max3_f32 v44, v4, v33, v43
	v_mov_b32_e32 v4, s50
	s_and_b64 vcc, s[8:9], vcc
	v_or_b32_e32 v66, 17, v70
	v_cndmask_b32_e32 v46, v4, v46, vcc
	v_cmp_ge_i32_e32 vcc, v66, v32
	s_and_b64 vcc, s[8:9], vcc
	v_or_b32_e32 v67, 19, v70
	v_cndmask_b32_e32 v47, v215, v47, vcc
	v_max3_f32 v4, v44, v46, v47
	v_or_b32_e32 v44, 18, v70
	v_cmp_ge_i32_e32 vcc, v44, v32
	s_and_b64 vcc, s[8:9], vcc
	v_or_b32_e32 v76, 32, v70
	v_cndmask_b32_e32 v48, v215, v48, vcc
	v_cmp_ge_i32_e32 vcc, v67, v32
	s_and_b64 vcc, s[8:9], vcc
	v_or_b32_e32 v77, 33, v70
	v_cndmask_b32_e32 v49, v215, v49, vcc
	v_cmp_ge_i32_e32 vcc, v76, v32
	v_max3_f32 v71, v4, v48, v49
	v_mov_b32_e32 v4, s50
	s_and_b64 vcc, s[8:9], vcc
	v_cndmask_b32_e32 v50, v4, v50, vcc
	v_cmp_ge_i32_e32 vcc, v77, v32
	s_and_b64 vcc, s[8:9], vcc
	v_or_b32_e32 v78, 35, v70
	v_cndmask_b32_e32 v51, v215, v51, vcc
	v_max3_f32 v4, v71, v50, v51
	v_or_b32_e32 v71, 34, v70
	v_cmp_ge_i32_e32 vcc, v71, v32
	s_and_b64 vcc, s[8:9], vcc
	v_or_b32_e32 v80, 48, v70
	v_cndmask_b32_e32 v52, v215, v52, vcc
	v_cmp_ge_i32_e32 vcc, v78, v32
	s_and_b64 vcc, s[8:9], vcc
	v_or_b32_e32 v81, 49, v70
	v_cndmask_b32_e32 v53, v215, v53, vcc
	v_cmp_ge_i32_e32 vcc, v80, v32
	v_max3_f32 v79, v4, v52, v53
	v_mov_b32_e32 v4, s50
	s_and_b64 vcc, s[8:9], vcc
	v_cndmask_b32_e32 v34, v4, v34, vcc
	v_cmp_ge_i32_e32 vcc, v81, v32
	s_and_b64 vcc, s[8:9], vcc
	v_or_b32_e32 v82, 51, v70
	v_cndmask_b32_e32 v35, v215, v35, vcc
	v_max3_f32 v4, v79, v34, v35
	v_or_b32_e32 v79, 50, v70
	v_cmp_ge_i32_e32 vcc, v79, v32
	s_and_b64 vcc, s[8:9], vcc
	v_or_b32_e32 v84, 64, v70
	v_cndmask_b32_e32 v36, v215, v36, vcc
	v_cmp_ge_i32_e32 vcc, v82, v32
	s_and_b64 vcc, s[8:9], vcc
	v_or_b32_e32 v85, 0x41, v70
	v_cndmask_b32_e32 v37, v215, v37, vcc
	v_cmp_ge_i32_e32 vcc, v84, v32
	v_max3_f32 v83, v4, v36, v37
	v_mov_b32_e32 v4, s50
	s_and_b64 vcc, s[8:9], vcc
	v_cndmask_b32_e32 v38, v4, v38, vcc
	v_cmp_ge_i32_e32 vcc, v85, v32
	s_and_b64 vcc, s[8:9], vcc
	v_or_b32_e32 v86, 0x43, v70
	v_cndmask_b32_e32 v39, v215, v39, vcc
	v_max3_f32 v4, v83, v38, v39
	v_or_b32_e32 v83, 0x42, v70
	v_cmp_ge_i32_e32 vcc, v83, v32
	s_and_b64 vcc, s[8:9], vcc
	v_or_b32_e32 v88, 0x50, v70
	v_cndmask_b32_e32 v40, v215, v40, vcc
	v_cmp_ge_i32_e32 vcc, v86, v32
	s_and_b64 vcc, s[8:9], vcc
	v_or_b32_e32 v92, 0x60, v70
	v_cndmask_b32_e32 v41, v215, v41, vcc
	v_cmp_ge_i32_e32 vcc, v88, v32
	v_max3_f32 v87, v4, v40, v41
	v_mov_b32_e32 v4, s50
	s_and_b64 vcc, s[8:9], vcc
	v_cndmask_b32_e32 v89, v4, v54, vcc
	v_or_b32_e32 v54, 0x51, v70
	v_cmp_ge_i32_e32 vcc, v54, v32
	s_and_b64 vcc, s[8:9], vcc
	s_nop 0
	v_cndmask_b32_e32 v90, v215, v55, vcc
	v_or_b32_e32 v55, 0x52, v70
	v_cmp_ge_i32_e32 vcc, v55, v32
	s_and_b64 vcc, s[8:9], vcc
	v_max3_f32 v4, v87, v89, v90
	v_cndmask_b32_e32 v87, v215, v56, vcc
	v_or_b32_e32 v56, 0x53, v70
	v_cmp_ge_i32_e32 vcc, v56, v32
	s_and_b64 vcc, s[8:9], vcc
	s_nop 0
	v_cndmask_b32_e32 v91, v215, v57, vcc
	v_cmp_ge_i32_e32 vcc, v92, v32
	v_max3_f32 v57, v4, v87, v91
	v_mov_b32_e32 v4, s50
	s_and_b64 vcc, s[8:9], vcc
	v_cndmask_b32_e32 v93, v4, v58, vcc
	v_or_b32_e32 v58, 0x61, v70
	v_cmp_ge_i32_e32 vcc, v58, v32
	s_and_b64 vcc, s[8:9], vcc
	s_nop 0
	v_cndmask_b32_e32 v94, v215, v59, vcc
	v_max3_f32 v4, v57, v93, v94
	v_or_b32_e32 v57, 0x62, v70
	v_cmp_ge_i32_e32 vcc, v57, v32
	s_and_b64 vcc, s[8:9], vcc
	v_or_b32_e32 v59, 0x63, v70
	v_cndmask_b32_e32 v95, v215, v60, vcc
	v_cmp_ge_i32_e32 vcc, v59, v32
	s_and_b64 vcc, s[8:9], vcc
	s_nop 0
	v_cndmask_b32_e32 v96, v215, v61, vcc
	v_or_b32_e32 v61, 0x70, v70
	v_cmp_ge_i32_e32 vcc, v61, v32
	v_max3_f32 v60, v4, v95, v96
	v_mov_b32_e32 v4, s50
	s_and_b64 vcc, s[8:9], vcc
	v_cndmask_b32_e32 v97, v4, v62, vcc
	v_or_b32_e32 v62, 0x71, v70
	v_cmp_ge_i32_e32 vcc, v62, v32
	s_and_b64 vcc, s[8:9], vcc
	s_nop 0
	v_cndmask_b32_e32 v98, v215, v63, vcc
	v_max3_f32 v4, v60, v97, v98
	v_or_b32_e32 v60, 0x72, v70
	v_cmp_ge_i32_e32 vcc, v60, v32
	s_and_b64 vcc, s[8:9], vcc
	v_or_b32_e32 v63, 0x73, v70
	v_cndmask_b32_e32 v99, v215, v64, vcc
	v_cmp_ge_i32_e32 vcc, v63, v32
	s_and_b64 vcc, s[8:9], vcc
	s_nop 0
	v_cndmask_b32_e32 v100, v215, v65, vcc
	v_max3_f32 v64, v4, v99, v100
	v_mov_b32_e32 v4, s50
	v_cmp_gt_i32_e32 vcc, v70, v32
	s_nop 1
	v_cndmask_b32_e32 v4, v72, v4, vcc
	v_cmp_lt_i32_e32 vcc, v70, v32
	s_nop 1
	v_cndmask_b32_e32 v72, v4, v72, vcc
	v_cndmask_b32_e32 v73, v215, v73, vcc
	v_cmp_le_i32_e32 vcc, v7, v32
	v_max3_f32 v4, v64, v4, v73
	s_nop 0
	v_cndmask_b32_e32 v7, v215, v74, vcc
	v_cmp_le_i32_e32 vcc, v42, v32
	s_nop 1
	v_cndmask_b32_e32 v74, v215, v75, vcc
	v_max3_f32 v42, v4, v7, v74
	v_mov_b32_e32 v4, s50
	v_cmp_gt_i32_e32 vcc, v45, v32
	s_nop 1
	v_cndmask_b32_e32 v16, v16, v4, vcc
	v_cmp_le_i32_e32 vcc, v66, v32
	s_nop 1
	v_cndmask_b32_e32 v17, v215, v17, vcc
	v_cmp_le_i32_e32 vcc, v44, v32
	v_max3_f32 v4, v42, v16, v17
	s_nop 0
	v_cndmask_b32_e32 v18, v215, v18, vcc
	v_cmp_le_i32_e32 vcc, v67, v32
	s_nop 1
	v_cndmask_b32_e32 v19, v215, v19, vcc
	v_max3_f32 v42, v4, v18, v19
	v_mov_b32_e32 v4, s50
	v_cmp_gt_i32_e32 vcc, v76, v32
	s_nop 1
	v_cndmask_b32_e32 v12, v12, v4, vcc
	v_cmp_le_i32_e32 vcc, v77, v32
	s_nop 1
	v_cndmask_b32_e32 v13, v215, v13, vcc
	v_cmp_le_i32_e32 vcc, v71, v32
	v_max3_f32 v4, v42, v12, v13
	s_nop 0
	v_cndmask_b32_e32 v14, v215, v14, vcc
	v_cmp_le_i32_e32 vcc, v78, v32
	s_nop 1
	v_cndmask_b32_e32 v15, v215, v15, vcc
	v_max3_f32 v42, v4, v14, v15
	v_mov_b32_e32 v4, s50
	v_cmp_gt_i32_e32 vcc, v80, v32
	s_nop 1
	v_cndmask_b32_e32 v8, v8, v4, vcc
	v_cmp_le_i32_e32 vcc, v81, v32
	s_nop 1
	v_cndmask_b32_e32 v71, v215, v9, vcc
	v_cmp_le_i32_e32 vcc, v79, v32
	v_max3_f32 v4, v42, v8, v71
	s_nop 0
	v_cndmask_b32_e32 v10, v215, v10, vcc
	v_cmp_le_i32_e32 vcc, v82, v32
	s_nop 1
	v_cndmask_b32_e32 v11, v215, v11, vcc
	v_max3_f32 v9, v4, v10, v11
	v_mov_b32_e32 v4, s50
	v_cmp_gt_i32_e32 vcc, v84, v32
	s_nop 1
	v_cndmask_b32_e32 v75, v28, v4, vcc
	v_cmp_le_i32_e32 vcc, v85, v32
	s_nop 1
	v_cndmask_b32_e32 v76, v215, v29, vcc
	v_cmp_le_i32_e32 vcc, v83, v32
	v_max3_f32 v4, v9, v75, v76
	s_nop 0
	v_cndmask_b32_e32 v77, v215, v30, vcc
	v_cmp_le_i32_e32 vcc, v86, v32
	s_nop 1
	v_cndmask_b32_e32 v78, v215, v31, vcc
	v_max3_f32 v9, v4, v77, v78
	v_mov_b32_e32 v4, s50
	v_cmp_gt_i32_e32 vcc, v88, v32
	s_nop 1
	v_cndmask_b32_e32 v79, v20, v4, vcc
	v_cmp_le_i32_e32 vcc, v54, v32
	s_nop 1
	v_cndmask_b32_e32 v80, v215, v21, vcc
	v_cmp_le_i32_e32 vcc, v55, v32
	v_max3_f32 v4, v9, v79, v80
	s_nop 0
	v_cndmask_b32_e32 v81, v215, v22, vcc
	v_cmp_le_i32_e32 vcc, v56, v32
	s_nop 1
	v_cndmask_b32_e32 v82, v215, v23, vcc
	v_max3_f32 v9, v4, v81, v82
	v_mov_b32_e32 v4, s50
	v_cmp_gt_i32_e32 vcc, v92, v32
	s_nop 1
	v_cndmask_b32_e32 v83, v24, v4, vcc
	v_cmp_le_i32_e32 vcc, v58, v32
	s_nop 1
	v_cndmask_b32_e32 v84, v215, v25, vcc
	v_cmp_le_i32_e32 vcc, v57, v32
	v_max3_f32 v4, v9, v83, v84
	s_nop 0
	v_cndmask_b32_e32 v85, v215, v26, vcc
	v_cmp_le_i32_e32 vcc, v59, v32
	s_nop 1
	v_cndmask_b32_e32 v86, v215, v27, vcc
	v_max3_f32 v9, v4, v85, v86
	v_mov_b32_e32 v4, s50
	v_cmp_gt_i32_e32 vcc, v61, v32
	s_nop 1
	v_cndmask_b32_e32 v0, v0, v4, vcc
	v_cmp_le_i32_e32 vcc, v62, v32
	s_nop 1
	v_cndmask_b32_e32 v1, v215, v1, vcc
	v_cmp_le_i32_e32 vcc, v60, v32
	v_max3_f32 v4, v9, v0, v1
	s_nop 0
	v_cndmask_b32_e32 v88, v215, v2, vcc
	v_cmp_le_i32_e32 vcc, v63, v32
	s_nop 1
	v_cndmask_b32_e32 v92, v215, v3, vcc
	v_max3_f32 v2, v4, v88, v92
	v_and_b32_e32 v4, 64, v193
	v_xor_b32_e32 v3, 16, v193
	v_add_u32_e32 v4, 64, v4
	v_cmp_lt_i32_e32 vcc, v3, v4
	s_nop 1
	v_cndmask_b32_e32 v3, v193, v3, vcc
	v_lshlrev_b32_e32 v101, 2, v3
	ds_bpermute_b32 v3, v101, v2
	s_waitcnt lgkmcnt(0)
	v_max_f32_e32 v3, v3, v3
	v_max_f32_e32 v2, v2, v3
	v_xor_b32_e32 v3, 32, v193
	v_cmp_lt_i32_e32 vcc, v3, v4
	s_nop 1
	v_cndmask_b32_e32 v3, v193, v3, vcc
	v_lshlrev_b32_e32 v102, 2, v3
	ds_bpermute_b32 v3, v102, v2
	s_waitcnt lgkmcnt(0)
	v_max_f32_e32 v3, v3, v3
	v_max_f32_e32 v9, v2, v3
	v_sub_f32_e32 v3, v46, v9
	v_mul_f32_e32 v3, 0x3fb8aa3b, v3
	v_exp_f32_e32 v66, v3
	v_sub_f32_e32 v3, v47, v9
	v_mul_f32_e32 v3, 0x3fb8aa3b, v3
	v_exp_f32_e32 v67, v3
	v_sub_f32_e32 v3, v48, v9
	v_mul_f32_e32 v3, 0x3fb8aa3b, v3
	v_exp_f32_e32 v60, v3
	v_sub_f32_e32 v3, v49, v9
	v_mul_f32_e32 v3, 0x3fb8aa3b, v3
	v_exp_f32_e32 v61, v3
	v_sub_f32_e32 v3, v50, v9
	v_mul_f32_e32 v3, 0x3fb8aa3b, v3
	v_exp_f32_e32 v54, v3
	v_sub_f32_e32 v3, v51, v9
	v_mul_f32_e32 v3, 0x3fb8aa3b, v3
	v_exp_f32_e32 v55, v3
	v_sub_f32_e32 v3, v52, v9
	v_mul_f32_e32 v3, 0x3fb8aa3b, v3
	v_exp_f32_e32 v56, v3
	v_sub_f32_e32 v3, v53, v9
	v_mul_f32_e32 v3, 0x3fb8aa3b, v3
	v_exp_f32_e32 v57, v3
	v_sub_f32_e32 v3, v34, v9
	v_mul_f32_e32 v3, 0x3fb8aa3b, v3
	v_exp_f32_e32 v58, v3
	v_sub_f32_e32 v3, v35, v9
	v_mul_f32_e32 v3, 0x3fb8aa3b, v3
	v_exp_f32_e32 v59, v3
	v_sub_f32_e32 v3, v36, v9
	v_mul_f32_e32 v3, 0x3fb8aa3b, v3
	v_exp_f32_e32 v52, v3
	v_sub_f32_e32 v3, v37, v9
	v_mul_f32_e32 v3, 0x3fb8aa3b, v3
	v_exp_f32_e32 v53, v3
	v_sub_f32_e32 v3, v38, v9
	v_mul_f32_e32 v3, 0x3fb8aa3b, v3
	v_exp_f32_e32 v46, v3
	v_sub_f32_e32 v3, v39, v9
	v_mul_f32_e32 v3, 0x3fb8aa3b, v3
	v_exp_f32_e32 v47, v3
	v_sub_f32_e32 v3, v40, v9
	v_mul_f32_e32 v3, 0x3fb8aa3b, v3
	v_exp_f32_e32 v48, v3
	v_sub_f32_e32 v3, v41, v9
	v_mul_f32_e32 v3, 0x3fb8aa3b, v3
	v_exp_f32_e32 v49, v3
	v_sub_f32_e32 v3, v89, v9
	v_mul_f32_e32 v3, 0x3fb8aa3b, v3
	v_exp_f32_e32 v50, v3
	v_sub_f32_e32 v3, v90, v9
	v_mul_f32_e32 v3, 0x3fb8aa3b, v3
	v_exp_f32_e32 v51, v3
	v_sub_f32_e32 v3, v87, v9
	v_mul_f32_e32 v3, 0x3fb8aa3b, v3
	v_exp_f32_e32 v44, v3
	v_sub_f32_e32 v3, v91, v9
	v_mul_f32_e32 v3, 0x3fb8aa3b, v3
	v_exp_f32_e32 v45, v3
	v_sub_f32_e32 v3, v93, v9
	v_mul_f32_e32 v3, 0x3fb8aa3b, v3
	v_exp_f32_e32 v38, v3
	v_sub_f32_e32 v3, v94, v9
	v_mul_f32_e32 v3, 0x3fb8aa3b, v3
	v_sub_f32_e32 v2, v5, v9
	v_exp_f32_e32 v39, v3
	v_sub_f32_e32 v3, v95, v9
	v_mul_f32_e32 v2, 0x3fb8aa3b, v2
	v_mul_f32_e32 v3, 0x3fb8aa3b, v3
	v_exp_f32_e32 v62, v2
	v_sub_f32_e32 v2, v6, v9
	v_exp_f32_e32 v40, v3
	v_sub_f32_e32 v3, v96, v9
	v_mul_f32_e32 v2, 0x3fb8aa3b, v2
	v_mul_f32_e32 v3, 0x3fb8aa3b, v3
	v_exp_f32_e32 v63, v2
	v_sub_f32_e32 v2, v33, v9
	v_exp_f32_e32 v41, v3
	v_sub_f32_e32 v3, v97, v9
	v_mul_f32_e32 v2, 0x3fb8aa3b, v2
	v_mul_f32_e32 v3, 0x3fb8aa3b, v3
	v_exp_f32_e32 v64, v2
	v_sub_f32_e32 v2, v43, v9
	v_exp_f32_e32 v42, v3
	v_sub_f32_e32 v3, v98, v9
	v_mul_f32_e32 v2, 0x3fb8aa3b, v2
	v_mul_f32_e32 v3, 0x3fb8aa3b, v3
	v_exp_f32_e32 v65, v2
	v_exp_f32_e32 v43, v3
	v_sub_f32_e32 v3, v99, v9
	v_add_f32_e32 v2, 0, v62
	v_mul_f32_e32 v3, 0x3fb8aa3b, v3
	v_add_f32_e32 v2, v63, v2
	v_exp_f32_e32 v36, v3
	v_sub_f32_e32 v3, v100, v9
	v_add_f32_e32 v2, v64, v2
	v_mul_f32_e32 v3, 0x3fb8aa3b, v3
	v_add_f32_e32 v2, v65, v2
	v_exp_f32_e32 v37, v3
	v_sub_f32_e32 v3, v72, v9
	v_add_f32_e32 v2, v66, v2
	v_mul_f32_e32 v3, 0x3fb8aa3b, v3
	v_add_f32_e32 v2, v67, v2
	v_exp_f32_e32 v28, v3
	v_sub_f32_e32 v3, v73, v9
	v_add_f32_e32 v2, v60, v2
	v_mul_f32_e32 v3, 0x3fb8aa3b, v3
	v_add_f32_e32 v2, v61, v2
	v_exp_f32_e32 v29, v3
	v_sub_f32_e32 v3, v7, v9
	v_add_f32_e32 v2, v54, v2
	v_mul_f32_e32 v3, 0x3fb8aa3b, v3
	v_add_f32_e32 v2, v55, v2
	v_exp_f32_e32 v30, v3
	v_sub_f32_e32 v3, v74, v9
	v_add_f32_e32 v2, v56, v2
	v_mul_f32_e32 v3, 0x3fb8aa3b, v3
	v_add_f32_e32 v2, v57, v2
	v_exp_f32_e32 v31, v3
	v_sub_f32_e32 v3, v16, v9
	v_add_f32_e32 v2, v58, v2
	v_mul_f32_e32 v3, 0x3fb8aa3b, v3
	v_add_f32_e32 v2, v59, v2
	v_exp_f32_e32 v34, v3
	v_sub_f32_e32 v3, v17, v9
	v_add_f32_e32 v2, v52, v2
	v_mul_f32_e32 v3, 0x3fb8aa3b, v3
	v_add_f32_e32 v2, v53, v2
	v_exp_f32_e32 v35, v3
	v_sub_f32_e32 v3, v18, v9
	v_add_f32_e32 v2, v46, v2
	v_mul_f32_e32 v3, 0x3fb8aa3b, v3
	v_add_f32_e32 v2, v47, v2
	v_exp_f32_e32 v26, v3
	v_sub_f32_e32 v3, v19, v9
	v_add_f32_e32 v2, v48, v2
	v_mul_f32_e32 v3, 0x3fb8aa3b, v3
	v_add_f32_e32 v2, v49, v2
	v_exp_f32_e32 v27, v3
	v_sub_f32_e32 v3, v12, v9
	v_add_f32_e32 v2, v50, v2
	v_mul_f32_e32 v3, 0x3fb8aa3b, v3
	v_add_f32_e32 v2, v51, v2
	v_exp_f32_e32 v20, v3
	v_sub_f32_e32 v3, v13, v9
	v_add_f32_e32 v2, v44, v2
	v_mul_f32_e32 v3, 0x3fb8aa3b, v3
	v_add_f32_e32 v2, v45, v2
	v_exp_f32_e32 v21, v3
	v_sub_f32_e32 v3, v14, v9
	v_add_f32_e32 v2, v38, v2
	v_mul_f32_e32 v3, 0x3fb8aa3b, v3
	v_add_f32_e32 v2, v39, v2
	v_exp_f32_e32 v22, v3
	v_sub_f32_e32 v3, v15, v9
	v_add_f32_e32 v2, v40, v2
	v_mul_f32_e32 v3, 0x3fb8aa3b, v3
	v_add_f32_e32 v2, v41, v2
	v_exp_f32_e32 v23, v3
	v_sub_f32_e32 v3, v8, v9
	v_add_f32_e32 v2, v42, v2
	v_mul_f32_e32 v3, 0x3fb8aa3b, v3
	v_add_f32_e32 v2, v43, v2
	v_exp_f32_e32 v24, v3
	v_sub_f32_e32 v3, v71, v9
	v_add_f32_e32 v2, v36, v2
	v_mul_f32_e32 v3, 0x3fb8aa3b, v3
	v_add_f32_e32 v2, v37, v2
	v_exp_f32_e32 v25, v3
	v_sub_f32_e32 v3, v10, v9
	v_add_f32_e32 v2, v28, v2
	v_mul_f32_e32 v3, 0x3fb8aa3b, v3
	v_add_f32_e32 v2, v29, v2
	v_exp_f32_e32 v18, v3
	v_sub_f32_e32 v3, v11, v9
	v_add_f32_e32 v2, v30, v2
	v_mul_f32_e32 v3, 0x3fb8aa3b, v3
	v_add_f32_e32 v2, v31, v2
	v_exp_f32_e32 v19, v3
	v_sub_f32_e32 v3, v75, v9
	v_add_f32_e32 v2, v34, v2
	v_mul_f32_e32 v3, 0x3fb8aa3b, v3
	v_add_f32_e32 v2, v35, v2
	v_exp_f32_e32 v12, v3
	v_sub_f32_e32 v3, v76, v9
	v_add_f32_e32 v2, v26, v2
	v_mul_f32_e32 v3, 0x3fb8aa3b, v3
	v_add_f32_e32 v2, v27, v2
	v_exp_f32_e32 v13, v3
	v_sub_f32_e32 v3, v77, v9
	v_add_f32_e32 v2, v20, v2
	v_mul_f32_e32 v3, 0x3fb8aa3b, v3
	v_add_f32_e32 v2, v21, v2
	v_exp_f32_e32 v14, v3
	v_sub_f32_e32 v3, v78, v9
	v_add_f32_e32 v2, v22, v2
	v_mul_f32_e32 v3, 0x3fb8aa3b, v3
	v_add_f32_e32 v2, v23, v2
	v_exp_f32_e32 v15, v3
	v_sub_f32_e32 v3, v79, v9
	v_add_f32_e32 v2, v24, v2
	v_mul_f32_e32 v3, 0x3fb8aa3b, v3
	v_add_f32_e32 v2, v25, v2
	v_exp_f32_e32 v16, v3
	v_sub_f32_e32 v3, v80, v9
	v_add_f32_e32 v2, v18, v2
	v_mul_f32_e32 v3, 0x3fb8aa3b, v3
	v_add_f32_e32 v2, v19, v2
	v_exp_f32_e32 v17, v3
	v_sub_f32_e32 v3, v81, v9
	v_add_f32_e32 v2, v12, v2
	v_mul_f32_e32 v3, 0x3fb8aa3b, v3
	v_add_f32_e32 v2, v13, v2
	v_exp_f32_e32 v10, v3
	v_sub_f32_e32 v3, v82, v9
	v_add_f32_e32 v2, v14, v2
	v_mul_f32_e32 v3, 0x3fb8aa3b, v3
	v_add_f32_e32 v2, v15, v2
	v_exp_f32_e32 v11, v3
	v_add_f32_e32 v2, v16, v2
	v_add_f32_e32 v2, v17, v2
	v_add_f32_e32 v2, v10, v2
	v_add_f32_e32 v6, v11, v2
	v_sub_f32_e32 v2, v83, v9
	v_mul_f32_e32 v2, 0x3fb8aa3b, v2
	v_sub_f32_e32 v3, v84, v9
	v_exp_f32_e32 v2, v2
	v_mul_f32_e32 v3, 0x3fb8aa3b, v3
	v_sub_f32_e32 v4, v85, v9
	v_exp_f32_e32 v3, v3
	v_mul_f32_e32 v4, 0x3fb8aa3b, v4
	v_sub_f32_e32 v5, v86, v9
	v_exp_f32_e32 v4, v4
	v_mul_f32_e32 v5, 0x3fb8aa3b, v5
	v_exp_f32_e32 v5, v5
	v_add_f32_e32 v6, v2, v6
	v_add_f32_e32 v6, v3, v6
	v_sub_f32_e32 v0, v0, v9
	v_add_f32_e32 v6, v4, v6
	v_mul_f32_e32 v0, 0x3fb8aa3b, v0
	v_add_f32_e32 v8, v5, v6
	v_exp_f32_e32 v6, v0
	v_sub_f32_e32 v0, v1, v9
	v_mul_f32_e32 v0, 0x3fb8aa3b, v0
	v_exp_f32_e32 v7, v0
	v_sub_f32_e32 v0, v88, v9
	v_mul_f32_e32 v0, 0x3fb8aa3b, v0
	v_sub_f32_e32 v1, v92, v9
	v_exp_f32_e32 v0, v0
	v_mul_f32_e32 v1, 0x3fb8aa3b, v1
	v_exp_f32_e32 v1, v1
	v_add_f32_e32 v8, v6, v8
	v_add_f32_e32 v8, v7, v8
	v_add_f32_e32 v8, v0, v8
	v_add_f32_e32 v8, v1, v8
	ds_bpermute_b32 v33, v101, v8
	s_waitcnt lgkmcnt(0)
	v_add_f32_e32 v8, v8, v33
	ds_bpermute_b32 v33, v102, v8
	s_waitcnt lgkmcnt(0)
	v_add_f32_e32 v33, v8, v33
	v_div_scale_f32 v8, s[8:9], v33, v33, 1.0
	v_rcp_f32_e32 v71, v8
	s_nop 0
	v_fma_f32 v72, -v8, v71, 1.0
	v_fmac_f32_e32 v71, v72, v71
	v_div_scale_f32 v72, vcc, 1.0, v33, 1.0
	v_mul_f32_e32 v73, v72, v71
	v_fma_f32 v74, -v8, v73, v72
	v_fmac_f32_e32 v73, v74, v71
	v_fma_f32 v8, -v8, v73, v72
	v_div_fmas_f32 v8, v8, v71, v73
	v_bfe_u32 v71, v69, 2, 2
	v_or_b32_e32 v70, v70, v71
	v_lshlrev_b32_e32 v69, 3, v69
	v_mul_u32_u24_e32 v70, 0xa0, v70
	v_and_b32_e32 v69, 24, v69
	v_add3_u32 v69, 16, v70, v69
	ds_read_b64_tr_b16 v[72:73], v69 offset:39424
	ds_read_b64_tr_b16 v[70:71], v69 offset:36864
	ds_read_b64_tr_b16 v[76:77], v69 offset:39456
	ds_read_b64_tr_b16 v[74:75], v69 offset:36896
	ds_read_b64_tr_b16 v[78:79], v69 offset:36928
	ds_read_b64_tr_b16 v[82:83], v69 offset:36960
	ds_read_b64_tr_b16 v[80:81], v69 offset:39488
	ds_read_b64_tr_b16 v[84:85], v69 offset:39520
	v_div_fixup_f32 v8, v8, v33, 1.0
	v_pk_mul_f32 v[62:63], v[62:63], v[8:9] op_sel_hi:[1,0]
	v_pk_mul_f32 v[64:65], v[64:65], v[8:9] op_sel_hi:[1,0]
	v_cvt_pk_bf16_f32 v62, v62, v63
	v_cvt_pk_bf16_f32 v63, v64, v65
	v_pk_mul_f32 v[64:65], v[66:67], v[8:9] op_sel_hi:[1,0]
	v_pk_mul_f32 v[60:61], v[60:61], v[8:9] op_sel_hi:[1,0]
	v_cvt_pk_bf16_f32 v64, v64, v65
	v_cvt_pk_bf16_f32 v65, v60, v61
	v_add_u32_e32 v60, 0x9000, v69
	s_waitcnt lgkmcnt(6)
	v_mfma_f32_16x16x32_bf16 v[70:73], v[70:73], v[62:65], 0
	s_waitcnt lgkmcnt(4)
	v_mfma_f32_16x16x32_bf16 v[74:77], v[74:77], v[62:65], 0
	s_waitcnt lgkmcnt(1)
	v_mfma_f32_16x16x32_bf16 v[78:81], v[78:81], v[62:65], 0
	s_waitcnt lgkmcnt(0)
	v_mfma_f32_16x16x32_bf16 v[62:65], v[82:85], v[62:65], 0
	ds_read_b64_tr_b16 v[84:85], v69 offset:44544
	ds_read_b64_tr_b16 v[82:83], v69 offset:41984
	ds_read_b64_tr_b16 v[88:89], v69 offset:44576
	ds_read_b64_tr_b16 v[86:87], v69 offset:42016
	ds_read_b64_tr_b16 v[90:91], v69 offset:42048
	ds_read_b64_tr_b16 v[94:95], v69 offset:42080
	ds_read_b64_tr_b16 v[92:93], v69 offset:44608
	ds_read_b64_tr_b16 v[96:97], v69 offset:44640
	v_pk_mul_f32 v[54:55], v[54:55], v[8:9] op_sel_hi:[1,0]
	v_pk_mul_f32 v[56:57], v[56:57], v[8:9] op_sel_hi:[1,0]
	v_cvt_pk_bf16_f32 v54, v54, v55
	v_cvt_pk_bf16_f32 v55, v56, v57
	v_pk_mul_f32 v[56:57], v[58:59], v[8:9] op_sel_hi:[1,0]
	v_pk_mul_f32 v[52:53], v[52:53], v[8:9] op_sel_hi:[1,0]
	v_cvt_pk_bf16_f32 v56, v56, v57
	v_cvt_pk_bf16_f32 v57, v52, v53
	s_waitcnt lgkmcnt(6)
	s_nop 0
	v_mfma_f32_16x16x32_bf16 v[70:73], v[82:85], v[54:57], v[70:73]
	s_waitcnt lgkmcnt(4)
	v_mfma_f32_16x16x32_bf16 v[74:77], v[86:89], v[54:57], v[74:77]
	s_waitcnt lgkmcnt(1)
	v_mfma_f32_16x16x32_bf16 v[78:81], v[90:93], v[54:57], v[78:81]
	s_waitcnt lgkmcnt(0)
	v_mfma_f32_16x16x32_bf16 v[52:55], v[94:97], v[54:57], v[62:65]
	ds_read_b64_tr_b16 v[58:59], v69 offset:49664
	ds_read_b64_tr_b16 v[56:57], v69 offset:47104
	s_nop 0
	ds_read_b64_tr_b16 v[64:65], v69 offset:49696
	ds_read_b64_tr_b16 v[62:63], v69 offset:47136
	ds_read_b64_tr_b16 v[82:83], v69 offset:47168
	ds_read_b64_tr_b16 v[86:87], v69 offset:47200
	ds_read_b64_tr_b16 v[84:85], v69 offset:49728
	ds_read_b64_tr_b16 v[88:89], v69 offset:49760
	v_pk_mul_f32 v[46:47], v[46:47], v[8:9] op_sel_hi:[1,0]
	v_pk_mul_f32 v[48:49], v[48:49], v[8:9] op_sel_hi:[1,0]
	v_cvt_pk_bf16_f32 v46, v46, v47
	v_cvt_pk_bf16_f32 v47, v48, v49
	v_pk_mul_f32 v[48:49], v[50:51], v[8:9] op_sel_hi:[1,0]
	v_pk_mul_f32 v[44:45], v[44:45], v[8:9] op_sel_hi:[1,0]
	v_cvt_pk_bf16_f32 v48, v48, v49
	v_cvt_pk_bf16_f32 v49, v44, v45
	s_waitcnt lgkmcnt(6)
	s_nop 0
	v_mfma_f32_16x16x32_bf16 v[56:59], v[56:59], v[46:49], v[70:73]
	s_waitcnt lgkmcnt(4)
	v_mfma_f32_16x16x32_bf16 v[62:65], v[62:65], v[46:49], v[74:77]
	s_waitcnt lgkmcnt(1)
	v_mfma_f32_16x16x32_bf16 v[70:73], v[82:85], v[46:49], v[78:81]
	s_waitcnt lgkmcnt(0)
	v_mfma_f32_16x16x32_bf16 v[44:47], v[86:89], v[46:49], v[52:55]
	ds_read_b64_tr_b16 v[50:51], v69 offset:54784
	ds_read_b64_tr_b16 v[48:49], v69 offset:52224
	s_nop 0
	ds_read_b64_tr_b16 v[54:55], v69 offset:54816
	ds_read_b64_tr_b16 v[52:53], v69 offset:52256
	ds_read_b64_tr_b16 v[74:75], v69 offset:52288
	ds_read_b64_tr_b16 v[78:79], v69 offset:52320
	ds_read_b64_tr_b16 v[76:77], v69 offset:54848
	ds_read_b64_tr_b16 v[80:81], v69 offset:54880
	v_pk_mul_f32 v[38:39], v[38:39], v[8:9] op_sel_hi:[1,0]
	v_pk_mul_f32 v[40:41], v[40:41], v[8:9] op_sel_hi:[1,0]
	v_cvt_pk_bf16_f32 v38, v38, v39
	v_cvt_pk_bf16_f32 v39, v40, v41
	v_pk_mul_f32 v[40:41], v[42:43], v[8:9] op_sel_hi:[1,0]
	v_pk_mul_f32 v[36:37], v[36:37], v[8:9] op_sel_hi:[1,0]
	v_cvt_pk_bf16_f32 v40, v40, v41
	v_cvt_pk_bf16_f32 v41, v36, v37
	s_waitcnt lgkmcnt(6)
	s_nop 0
	v_mfma_f32_16x16x32_bf16 v[48:51], v[48:51], v[38:41], v[56:59]
	s_waitcnt lgkmcnt(4)
	v_mfma_f32_16x16x32_bf16 v[52:55], v[52:55], v[38:41], v[62:65]
	s_waitcnt lgkmcnt(1)
	v_mfma_f32_16x16x32_bf16 v[56:59], v[74:77], v[38:41], v[70:73]
	s_waitcnt lgkmcnt(0)
	v_mfma_f32_16x16x32_bf16 v[36:39], v[78:81], v[38:41], v[44:47]
	ds_read_b64_tr_b16 v[42:43], v69 offset:59904
	ds_read_b64_tr_b16 v[40:41], v69 offset:57344
	s_nop 0
	ds_read_b64_tr_b16 v[46:47], v69 offset:59936
	ds_read_b64_tr_b16 v[44:45], v69 offset:57376
	ds_read_b64_tr_b16 v[62:63], v69 offset:57408
	ds_read_b64_tr_b16 v[70:71], v69 offset:57440
	ds_read_b64_tr_b16 v[64:65], v69 offset:59968
	ds_read_b64_tr_b16 v[72:73], v69 offset:60000
	v_pk_mul_f32 v[28:29], v[28:29], v[8:9] op_sel_hi:[1,0]
	v_pk_mul_f32 v[30:31], v[30:31], v[8:9] op_sel_hi:[1,0]
	v_cvt_pk_bf16_f32 v28, v28, v29
	v_cvt_pk_bf16_f32 v29, v30, v31
	v_pk_mul_f32 v[30:31], v[34:35], v[8:9] op_sel_hi:[1,0]
	v_pk_mul_f32 v[26:27], v[26:27], v[8:9] op_sel_hi:[1,0]
	v_cvt_pk_bf16_f32 v30, v30, v31
	v_cvt_pk_bf16_f32 v31, v26, v27
	s_waitcnt lgkmcnt(6)
	s_nop 0
	v_mfma_f32_16x16x32_bf16 v[40:43], v[40:43], v[28:31], v[48:51]
	s_waitcnt lgkmcnt(4)
	v_mfma_f32_16x16x32_bf16 v[44:47], v[44:47], v[28:31], v[52:55]
	s_waitcnt lgkmcnt(1)
	v_mfma_f32_16x16x32_bf16 v[48:51], v[62:65], v[28:31], v[56:59]
	s_waitcnt lgkmcnt(0)
	v_mfma_f32_16x16x32_bf16 v[26:29], v[70:73], v[28:31], v[36:39]
	s_nop 2
	ds_read_b64_tr_b16 v[36:37], v69 offset:65024
	ds_read_b64_tr_b16 v[34:35], v69 offset:62464
	ds_read_b64_tr_b16 v[54:55], v69 offset:65056
	ds_read_b64_tr_b16 v[52:53], v69 offset:62496
	ds_read_b64_tr_b16 v[56:57], v69 offset:62528
	ds_read_b64_tr_b16 v[62:63], v69 offset:62560
	ds_read_b64_tr_b16 v[58:59], v69 offset:65088
	ds_read_b64_tr_b16 v[64:65], v69 offset:65120
	v_pk_mul_f32 v[20:21], v[20:21], v[8:9] op_sel_hi:[1,0]
	v_pk_mul_f32 v[22:23], v[22:23], v[8:9] op_sel_hi:[1,0]
	v_cvt_pk_bf16_f32 v20, v20, v21
	v_cvt_pk_bf16_f32 v21, v22, v23
	v_pk_mul_f32 v[22:23], v[24:25], v[8:9] op_sel_hi:[1,0]
	v_pk_mul_f32 v[18:19], v[18:19], v[8:9] op_sel_hi:[1,0]
	v_cvt_pk_bf16_f32 v22, v22, v23
	v_cvt_pk_bf16_f32 v23, v18, v19
	s_waitcnt lgkmcnt(6)
	s_nop 0
	v_mfma_f32_16x16x32_bf16 v[34:37], v[34:37], v[20:23], v[40:43]
	s_waitcnt lgkmcnt(4)
	v_mfma_f32_16x16x32_bf16 v[38:41], v[52:55], v[20:23], v[44:47]
	s_waitcnt lgkmcnt(1)
	v_mfma_f32_16x16x32_bf16 v[42:45], v[56:59], v[20:23], v[48:51]
	s_waitcnt lgkmcnt(0)
	v_mfma_f32_16x16x32_bf16 v[18:21], v[62:65], v[20:23], v[26:29]
	ds_read_b64_tr_b16 v[24:25], v60 offset:33280
	ds_read_b64_tr_b16 v[22:23], v60 offset:30720
	s_nop 0
	ds_read_b64_tr_b16 v[28:29], v60 offset:33312
	ds_read_b64_tr_b16 v[26:27], v60 offset:30752
	ds_read_b64_tr_b16 v[46:47], v60 offset:30784
	ds_read_b64_tr_b16 v[50:51], v60 offset:30816
	ds_read_b64_tr_b16 v[48:49], v60 offset:33344
	ds_read_b64_tr_b16 v[52:53], v60 offset:33376
	v_pk_mul_f32 v[12:13], v[12:13], v[8:9] op_sel_hi:[1,0]
	v_pk_mul_f32 v[14:15], v[14:15], v[8:9] op_sel_hi:[1,0]
	v_cvt_pk_bf16_f32 v12, v12, v13
	v_cvt_pk_bf16_f32 v13, v14, v15
	v_pk_mul_f32 v[14:15], v[16:17], v[8:9] op_sel_hi:[1,0]
	v_pk_mul_f32 v[10:11], v[10:11], v[8:9] op_sel_hi:[1,0]
	v_cvt_pk_bf16_f32 v14, v14, v15
	v_cvt_pk_bf16_f32 v15, v10, v11
	s_waitcnt lgkmcnt(6)
	s_nop 0
	v_mfma_f32_16x16x32_bf16 v[22:25], v[22:25], v[12:15], v[34:37]
	s_waitcnt lgkmcnt(4)
	v_mfma_f32_16x16x32_bf16 v[26:29], v[26:29], v[12:15], v[38:41]
	s_waitcnt lgkmcnt(1)
	v_mfma_f32_16x16x32_bf16 v[34:37], v[46:49], v[12:15], v[42:45]
	s_waitcnt lgkmcnt(0)
	v_mfma_f32_16x16x32_bf16 v[10:13], v[50:53], v[12:15], v[18:21]
	ds_read_b64_tr_b16 v[16:17], v60 offset:38400
	ds_read_b64_tr_b16 v[14:15], v60 offset:35840
	s_nop 0
	ds_read_b64_tr_b16 v[20:21], v60 offset:38432
	ds_read_b64_tr_b16 v[18:19], v60 offset:35872
	ds_read_b64_tr_b16 v[38:39], v60 offset:35904
	ds_read_b64_tr_b16 v[42:43], v60 offset:35936
	ds_read_b64_tr_b16 v[40:41], v60 offset:38464
	ds_read_b64_tr_b16 v[44:45], v60 offset:38496
	v_pk_mul_f32 v[2:3], v[2:3], v[8:9] op_sel_hi:[1,0]
	v_pk_mul_f32 v[4:5], v[4:5], v[8:9] op_sel_hi:[1,0]
	v_cvt_pk_bf16_f32 v2, v2, v3
	v_cvt_pk_bf16_f32 v3, v4, v5
	v_pk_mul_f32 v[4:5], v[6:7], v[8:9] op_sel_hi:[1,0]
	v_pk_mul_f32 v[0:1], v[0:1], v[8:9] op_sel_hi:[1,0]
	v_cvt_pk_bf16_f32 v4, v4, v5
	v_cvt_pk_bf16_f32 v5, v0, v1
	s_waitcnt lgkmcnt(6)
	s_nop 0
	v_mfma_f32_16x16x32_bf16 v[14:17], v[14:17], v[2:5], v[22:25]
	s_waitcnt lgkmcnt(4)
	v_mfma_f32_16x16x32_bf16 v[18:21], v[18:21], v[2:5], v[26:29]
	s_waitcnt lgkmcnt(1)
	v_mfma_f32_16x16x32_bf16 v[22:25], v[38:41], v[2:5], v[34:37]
	s_waitcnt lgkmcnt(0)
	v_mfma_f32_16x16x32_bf16 v[2:5], v[42:45], v[2:5], v[10:13]
	v_add_u32_e32 v0, s7, v32
	s_lshr_b32 s7, 0x2000, s5
	s_add_i32 s7, s7, -1
	v_and_b32_e32 v1, s7, v0
	s_sub_i32 s7, 13, s5
	v_ashrrev_i32_e32 v0, s7, v0
	v_lshl_add_u32 v0, v1, s5, v0
	s_ashr_i32 s7, s6, 31
	s_lshl_b64 s[6:7], s[6:7], 13
	v_ashrrev_i32_e32 v1, 31, v0
	v_lshl_add_u64 v[0:1], s[6:7], 0, v[0:1]
	v_mov_b64_e32 v[6:7], s[0:1]
	v_mad_u64_u32 v[6:7], s[6:7], v0, s53, v[6:7]
	s_lshl_b32 s6, s4, 6
	v_mad_i32_i24 v7, v1, s53, v7
	s_ashr_i32 s7, s6, 31
	v_lshl_add_u64 v[6:7], s[6:7], 1, v[6:7]
	v_lshl_add_u64 v[6:7], v[6:7], 0, v[136:137]
	s_mov_b64 s[6:7], 0x988da00
	s_mov_b32 s5, 0x988d000
	v_lshl_add_u64 v[10:11], v[6:7], 0, s[6:7]
	v_add_co_u32_e32 v6, vcc, s5, v6
	v_cvt_pk_bf16_f32 v12, v14, v15
	v_cvt_pk_bf16_f32 v13, v16, v17
	v_addc_co_u32_e32 v7, vcc, 0, v7, vcc
	flat_store_dwordx2 v[6:7], v[12:13] offset:2560
	v_cvt_pk_bf16_f32 v6, v18, v19
	v_cvt_pk_bf16_f32 v7, v20, v21
	flat_store_dwordx2 v[10:11], v[6:7] offset:32
	v_cvt_pk_bf16_f32 v6, v22, v23
	v_cvt_pk_bf16_f32 v7, v24, v25
	v_cvt_pk_bf16_f32 v2, v2, v3
	v_cvt_pk_bf16_f32 v3, v4, v5
	v_cmp_eq_u32_e32 vcc, 0, v68
	flat_store_dwordx2 v[10:11], v[6:7] offset:64
	flat_store_dwordx2 v[10:11], v[2:3] offset:96
	s_and_saveexec_b64 s[6:7], vcc
	s_cbranch_execz .LBB0_407
	v_cmp_gt_f32_e32 vcc, s27, v33
	s_ashr_i32 s5, s4, 31
	s_nop 0
	v_cndmask_b32_e64 v2, 0, 32, vcc
	v_ldexp_f32 v2, v33, v2
	v_log_f32_e32 v2, v2
	v_cndmask_b32_e32 v3, 0, v213, vcc
	v_mul_f32_e32 v4, 0x3f317217, v2
	v_fma_f32 v4, v2, s24, -v4
	v_fmac_f32_e32 v4, 0x3377d1cf, v2
	v_fmac_f32_e32 v4, 0x3f317217, v2
	v_cmp_lt_f32_e64 vcc, |v2|, s25
	s_nop 1
	v_cndmask_b32_e32 v2, v2, v4, vcc
	v_sub_f32_e32 v2, v2, v3
	v_add_f32_e32 v4, v9, v2
	v_mad_u64_u32 v[2:3], s[0:1], v0, 24, s[0:1]
	v_mad_i32_i24 v3, v1, 24, v3
	v_lshl_add_u64 v[0:1], s[4:5], 2, v[2:3]
	v_add_co_u32_e32 v0, vcc, 0xa54d000, v0
	s_nop 1
	v_addc_co_u32_e32 v1, vcc, 0, v1, vcc
	flat_store_dword v[0:1], v4 offset:2560
	s_branch .LBB0_407
